# sample chain rows published with write-through stores; chip-wide sample barrier arrival no longer writes the XCD L2 back
# speedup vs baseline: 1.0072x; 1.0072x over previous
.LBB11_500:
	s_or_b64 exec, exec, s[20:21]
	v_cmp_eq_u32_e32 vcc, 1, v0
	s_waitcnt vmcnt(0)
	v_readfirstlane_b32 s0, v4
	s_cbranch_vccnz .LBB11_538
	v_cvt_f32_u32_e32 v4, v2
	v_sub_u32_e32 v5, 0, v2
	v_add_u32_e32 v3, s0, v3
	v_rcp_iflag_f32_e32 v4, v4
	s_nop 0
	v_mul_f32_e32 v4, 0x4f7ffffe, v4
	v_cvt_u32_f32_e32 v4, v4
	v_mul_lo_u32 v5, v5, v4
	v_mul_hi_u32 v5, v4, v5
	v_add_u32_e32 v4, v4, v5
	v_mul_hi_u32 v4, v3, v4
	v_mul_lo_u32 v5, v4, v2
	v_sub_u32_e32 v5, v3, v5
	v_add_u32_e32 v6, 1, v4
	v_cmp_ge_u32_e32 vcc, v5, v2
	v_add_u32_e32 v3, 1, v3
	s_nop 0
	v_cndmask_b32_e32 v4, v4, v6, vcc
	v_sub_u32_e32 v6, v5, v2
	v_cndmask_b32_e32 v5, v5, v6, vcc
	v_add_u32_e32 v6, 1, v4
	v_cmp_ge_u32_e32 vcc, v5, v2
	s_nop 1
	v_cndmask_b32_e32 v4, v4, v6, vcc
	v_mul_lo_u32 v4, v2, v4
	v_add_u32_e32 v2, v4, v2
	v_cmp_eq_u32_e32 vcc, v3, v2
	s_and_saveexec_b64 s[18:19], vcc
	s_cbranch_execz .LBB11_537
	s_mov_b64 s[20:21], exec
	s_nop 0
	s_waitcnt lgkmcnt(0)
	s_waitcnt vmcnt(0)
	v_mbcnt_lo_u32_b32 v2, s20, 0
	v_mbcnt_hi_u32_b32 v2, s21, v2
	v_cmp_eq_u32_e32 vcc, 0, v2
	s_and_saveexec_b64 s[22:23], vcc
	s_cbranch_execz .LBB11_504
	s_bcnt1_i32_b64 s0, s[20:21]
	v_mov_b32_e32 v3, s0
	v_readlane_b32 s0, v247, 36
	v_readlane_b32 s1, v247, 37
	s_nop 4
	global_atomic_add v3, v1, v3, s[0:1] sc0

.LBB11_791:
	global_load_dword v44, v1, s[46:47]
	s_add_u32 s0, s88, 0x15900000
	s_addc_u32 s1, s89, 0
	s_add_u32 s6, s88, 0x11800000
	s_addc_u32 s7, s89, 0
	v_mov_b32_e32 v91, 0
	s_waitcnt vmcnt(0)
	v_fmamk_f32 v44, v44, 0x3a800000, v206
	v_cmp_gt_f32_e64 s[44:45], s77, v44
	v_mul_f32_e32 v45, 0x4b800000, v44
	s_nop 0
	v_cndmask_b32_e64 v44, v44, v45, s[44:45]
	v_rsq_f32_e32 v44, v44
	s_nop 0
	v_mul_f32_e32 v45, 0x45800000, v44
	v_cndmask_b32_e64 v112, v44, v45, s[44:45]
	s_waitcnt lgkmcnt(0)
	global_load_dwordx4 v[44:47], v1, s[0:1] offset:16
	global_load_dwordx4 v[48:51], v209, s[88:89]
	global_load_dwordx4 v[92:95], v1, s[6:7] offset:16
	global_load_dwordx4 v[52:55], v210, s[88:89]
	global_load_dwordx4 v[96:99], v1, s[56:57] offset:48
	global_load_dwordx4 v[100:103], v1, s[56:57] offset:32
	global_load_dwordx4 v[104:107], v1, s[56:57] offset:16
	global_load_dwordx4 v[108:111], v1, s[56:57]
	s_mov_b32 s0, 0x8100000
	s_waitcnt vmcnt(6)
	v_lshlrev_b32_e32 v56, 16, v48
	v_and_b32_e32 v57, 0xffff0000, v48
	s_waitcnt vmcnt(4)
	v_lshlrev_b32_e32 v58, 16, v52
	v_and_b32_e32 v59, 0xffff0000, v52
	v_lshlrev_b32_e32 v48, 16, v49
	v_and_b32_e32 v49, 0xffff0000, v49
	v_lshlrev_b32_e32 v52, 16, v53
	v_and_b32_e32 v53, 0xffff0000, v53
	v_pk_add_f32 v[56:57], v[56:57], v[58:59]
	v_pk_add_f32 v[48:49], v[48:49], v[52:53]
	v_pk_mul_f32 v[52:53], v[112:113], v[56:57] op_sel_hi:[0,1]
	v_pk_mul_f32 v[48:49], v[112:113], v[48:49] op_sel_hi:[0,1]
	s_waitcnt vmcnt(0)
	v_pk_mul_f32 v[56:57], v[110:111], v[48:49]
	v_pk_mul_f32 v[58:59], v[108:109], v[52:53]
	v_lshlrev_b32_e32 v48, 16, v50
	v_and_b32_e32 v49, 0xffff0000, v50
	v_lshlrev_b32_e32 v52, 16, v54
	v_and_b32_e32 v53, 0xffff0000, v54
	v_pk_add_f32 v[48:49], v[48:49], v[52:53]
	v_lshlrev_b32_e32 v50, 16, v51
	v_and_b32_e32 v51, 0xffff0000, v51
	v_lshlrev_b32_e32 v52, 16, v55
	v_and_b32_e32 v53, 0xffff0000, v55
	v_pk_add_f32 v[50:51], v[50:51], v[52:53]
	v_pk_mul_f32 v[48:49], v[112:113], v[48:49] op_sel_hi:[0,1]
	v_pk_mul_f32 v[50:51], v[112:113], v[50:51] op_sel_hi:[0,1]
	v_pk_mul_f32 v[52:53], v[106:107], v[50:51]
	v_pk_mul_f32 v[54:55], v[104:105], v[48:49]
	v_lshlrev_b32_e32 v48, 16, v44
	v_and_b32_e32 v49, 0xffff0000, v44
	v_lshlrev_b32_e32 v50, 16, v92
	v_and_b32_e32 v51, 0xffff0000, v92
	v_pk_add_f32 v[48:49], v[48:49], v[50:51]
	v_lshlrev_b32_e32 v44, 16, v45
	v_and_b32_e32 v45, 0xffff0000, v45
	v_lshlrev_b32_e32 v50, 16, v93
	v_and_b32_e32 v51, 0xffff0000, v93
	v_pk_add_f32 v[44:45], v[44:45], v[50:51]
	v_pk_mul_f32 v[50:51], v[112:113], v[48:49] op_sel_hi:[0,1]
	v_pk_mul_f32 v[44:45], v[112:113], v[44:45] op_sel_hi:[0,1]
	v_pk_mul_f32 v[48:49], v[102:103], v[44:45]
	v_lshlrev_b32_e32 v44, 16, v46
	v_and_b32_e32 v45, 0xffff0000, v46
	v_lshlrev_b32_e32 v92, 16, v94
	v_and_b32_e32 v93, 0xffff0000, v94
	v_pk_add_f32 v[44:45], v[44:45], v[92:93]
	v_lshlrev_b32_e32 v46, 16, v47
	v_and_b32_e32 v47, 0xffff0000, v47
	v_lshlrev_b32_e32 v92, 16, v95
	v_and_b32_e32 v93, 0xffff0000, v95
	v_pk_add_f32 v[46:47], v[46:47], v[92:93]
	v_pk_mul_f32 v[92:93], v[112:113], v[44:45] op_sel_hi:[0,1]
	v_lshl_add_u64 v[94:95], v[40:41], 0, s[90:91]
	v_pk_mul_f32 v[44:45], v[112:113], v[46:47] op_sel_hi:[0,1]
	v_pk_mul_f32 v[46:47], v[96:97], v[92:93]
	global_load_dword v96, v[94:95], off
	v_lshl_add_u64 v[94:95], v[38:39], 0, s[90:91]
	global_load_dword v94, v[94:95], off
	v_fma_f32 v93, v2, v58, 0
	v_fma_f32 v92, v3, v58, 0
	v_fmac_f32_e32 v93, v4, v59
	v_fmac_f32_e32 v92, v5, v59
	v_fmac_f32_e32 v93, v6, v56
	v_fmac_f32_e32 v92, v7, v56
	v_fmac_f32_e32 v93, v8, v57
	v_fmac_f32_e32 v92, v9, v57
	v_fmac_f32_e32 v93, v10, v54
	v_fmac_f32_e32 v92, v11, v54
	v_fmac_f32_e32 v93, v12, v55
	v_fmac_f32_e32 v92, v13, v55
	v_fmac_f32_e32 v93, v14, v52
	v_fmac_f32_e32 v92, v15, v52
	v_pk_mul_f32 v[50:51], v[100:101], v[50:51]
	v_fmac_f32_e32 v93, v16, v53
	v_fmac_f32_e32 v92, v17, v53
	v_fmac_f32_e32 v93, v18, v50
	v_fmac_f32_e32 v92, v19, v50
	v_fmac_f32_e32 v93, v20, v51
	v_fmac_f32_e32 v92, v21, v51
	v_fmac_f32_e32 v93, v22, v48
	v_fmac_f32_e32 v92, v23, v48
	v_fmac_f32_e32 v93, v24, v49
	v_fmac_f32_e32 v92, v25, v49
	v_fmac_f32_e32 v93, v26, v46
	v_fmac_f32_e32 v92, v27, v46
	v_pk_mul_f32 v[44:45], v[98:99], v[44:45]
	v_fmac_f32_e32 v93, v28, v47
	v_fmac_f32_e32 v92, v29, v47
	v_fmac_f32_e32 v93, v30, v44
	v_fmac_f32_e32 v92, v31, v44
	v_fmac_f32_e32 v93, v32, v45
	v_fmac_f32_e32 v92, v33, v45
	s_waitcnt vmcnt(0)
	v_mul_f32_e32 v95, v35, v94
	v_mul_f32_e32 v94, v34, v94
	v_fma_f32 v95, v34, v96, -v95
	v_fmac_f32_e32 v94, v35, v96
	v_add_f32_e32 v93, v95, v93
	v_add_f32_e32 v92, v94, v92
	v_lshl_add_u64 v[94:95], v[36:37], 0, s[90:91]
	v_add_co_u32_e64 v96, s[44:45], s0, v94
	s_mov_b32 s0, 0x8500000
	s_nop 0
	v_addc_co_u32_e64 v97, s[44:45], 0, v95, s[44:45]
	v_add_co_u32_e64 v94, s[44:45], s0, v94
	global_store_dword v[96:97], v93, off sc1
	s_nop 0
	v_addc_co_u32_e64 v95, s[44:45], 0, v95, s[44:45]
	global_store_dword v[94:95], v92, off sc1
	s_load_dwordx2 s[0:1], s[58:59], 0xc8
	s_lshl_b64 s[6:7], s[60:61], 2
	v_mbcnt_lo_u32_b32 v231, -1, 0
	v_mbcnt_hi_u32_b32 v231, -1, v231
	v_lshlrev_b32_e32 v231, 2, v231
	s_waitcnt lgkmcnt(0)
	s_add_u32 s0, s0, s6
	s_addc_u32 s1, s1, s7
	s_and_saveexec_b64 s[44:45], vcc
	global_load_dword v230, v231, s[0:1]
	s_or_b64 exec, exec, s[44:45]
	v_mul_f32_e32 v214, v67, v92
	v_fma_f32 v214, v0, v93, -v214
	v_mul_f32_e32 v215, v68, v92
	v_fma_f32 v215, v60, v93, -v215
	v_mul_f32_e32 v216, v69, v92
	v_fma_f32 v216, v61, v93, -v216
	v_mul_f32_e32 v217, v70, v92
	v_fma_f32 v217, v62, v93, -v217
	v_mul_f32_e32 v218, v71, v92
	v_fma_f32 v218, v63, v93, -v218
	v_mul_f32_e32 v219, v72, v92
	v_fma_f32 v219, v64, v93, -v219
	v_mul_f32_e32 v220, v73, v92
	v_fma_f32 v220, v65, v93, -v220
	v_mul_f32_e32 v221, v74, v92
	v_fma_f32 v221, v66, v93, -v221
	v_mul_f32_e32 v222, v83, v92
	v_fma_f32 v222, v75, v93, -v222
	v_mul_f32_e32 v223, v84, v92
	v_fma_f32 v223, v76, v93, -v223
	v_mul_f32_e32 v224, v85, v92
	v_fma_f32 v224, v77, v93, -v224
	v_mul_f32_e32 v225, v86, v92
	v_fma_f32 v225, v78, v93, -v225
	v_mul_f32_e32 v226, v87, v92
	v_fma_f32 v226, v79, v93, -v226
	v_mul_f32_e32 v227, v88, v92
	v_fma_f32 v227, v80, v93, -v227
	v_mul_f32_e32 v228, v89, v92
	v_fma_f32 v228, v81, v93, -v228
	v_mul_f32_e32 v229, v90, v92
	v_fma_f32 v229, v82, v93, -v229
	ds_bpermute_b32 v116, v200, v214
	ds_bpermute_b32 v117, v200, v215
	ds_bpermute_b32 v118, v200, v216
	ds_bpermute_b32 v119, v200, v217
	ds_bpermute_b32 v120, v200, v218
	ds_bpermute_b32 v121, v200, v219
	ds_bpermute_b32 v122, v200, v220
	ds_bpermute_b32 v123, v200, v221
	s_waitcnt lgkmcnt(7)
	v_add_f32_e32 v214, v214, v116
	s_waitcnt lgkmcnt(6)
	v_add_f32_e32 v215, v215, v117
	s_waitcnt lgkmcnt(5)
	v_add_f32_e32 v216, v216, v118
	s_waitcnt lgkmcnt(4)
	v_add_f32_e32 v217, v217, v119
	s_waitcnt lgkmcnt(3)
	v_add_f32_e32 v218, v218, v120
	s_waitcnt lgkmcnt(2)
	v_add_f32_e32 v219, v219, v121
	s_waitcnt lgkmcnt(1)
	v_add_f32_e32 v220, v220, v122
	s_waitcnt lgkmcnt(0)
	v_add_f32_e32 v221, v221, v123
	ds_bpermute_b32 v116, v201, v214
	ds_bpermute_b32 v117, v201, v215
	ds_bpermute_b32 v118, v201, v216
	ds_bpermute_b32 v119, v201, v217
	ds_bpermute_b32 v120, v201, v218
	ds_bpermute_b32 v121, v201, v219
	ds_bpermute_b32 v122, v201, v220
	ds_bpermute_b32 v123, v201, v221
	s_waitcnt lgkmcnt(7)
	v_add_f32_e32 v214, v214, v116
	s_waitcnt lgkmcnt(6)
	v_add_f32_e32 v215, v215, v117
	s_waitcnt lgkmcnt(5)
	v_add_f32_e32 v216, v216, v118
	s_waitcnt lgkmcnt(4)
	v_add_f32_e32 v217, v217, v119
	s_waitcnt lgkmcnt(3)
	v_add_f32_e32 v218, v218, v120
	s_waitcnt lgkmcnt(2)
	v_add_f32_e32 v219, v219, v121
	s_waitcnt lgkmcnt(1)
	v_add_f32_e32 v220, v220, v122
	s_waitcnt lgkmcnt(0)
	v_add_f32_e32 v221, v221, v123
	ds_bpermute_b32 v116, v202, v214
	ds_bpermute_b32 v117, v202, v215
	ds_bpermute_b32 v118, v202, v216
	ds_bpermute_b32 v119, v202, v217
	ds_bpermute_b32 v120, v202, v218
	ds_bpermute_b32 v121, v202, v219
	ds_bpermute_b32 v122, v202, v220
	ds_bpermute_b32 v123, v202, v221
	s_waitcnt lgkmcnt(7)
	v_add_f32_e32 v214, v214, v116
	s_waitcnt lgkmcnt(6)
	v_add_f32_e32 v215, v215, v117
	s_waitcnt lgkmcnt(5)
	v_add_f32_e32 v216, v216, v118
	s_waitcnt lgkmcnt(4)
	v_add_f32_e32 v217, v217, v119
	s_waitcnt lgkmcnt(3)
	v_add_f32_e32 v218, v218, v120
	s_waitcnt lgkmcnt(2)
	v_add_f32_e32 v219, v219, v121
	s_waitcnt lgkmcnt(1)
	v_add_f32_e32 v220, v220, v122
	s_waitcnt lgkmcnt(0)
	v_add_f32_e32 v221, v221, v123
	ds_bpermute_b32 v116, v203, v214
	ds_bpermute_b32 v117, v203, v215
	ds_bpermute_b32 v118, v203, v216
	ds_bpermute_b32 v119, v203, v217
	ds_bpermute_b32 v120, v203, v218
	ds_bpermute_b32 v121, v203, v219
	ds_bpermute_b32 v122, v203, v220
	ds_bpermute_b32 v123, v203, v221
	s_waitcnt lgkmcnt(7)
	v_add_f32_e32 v214, v214, v116
	s_waitcnt lgkmcnt(6)
	v_add_f32_e32 v215, v215, v117
	s_waitcnt lgkmcnt(5)
	v_add_f32_e32 v216, v216, v118
	s_waitcnt lgkmcnt(4)
	v_add_f32_e32 v217, v217, v119
	s_waitcnt lgkmcnt(3)
	v_add_f32_e32 v218, v218, v120
	s_waitcnt lgkmcnt(2)
	v_add_f32_e32 v219, v219, v121
	s_waitcnt lgkmcnt(1)
	v_add_f32_e32 v220, v220, v122
	s_waitcnt lgkmcnt(0)
	v_add_f32_e32 v221, v221, v123
	ds_bpermute_b32 v116, v204, v214
	ds_bpermute_b32 v117, v204, v215
	ds_bpermute_b32 v118, v204, v216
	ds_bpermute_b32 v119, v204, v217
	ds_bpermute_b32 v120, v204, v218
	ds_bpermute_b32 v121, v204, v219
	ds_bpermute_b32 v122, v204, v220
	ds_bpermute_b32 v123, v204, v221
	s_waitcnt lgkmcnt(7)
	v_add_f32_e32 v214, v214, v116
	s_waitcnt lgkmcnt(6)
	v_add_f32_e32 v215, v215, v117
	s_waitcnt lgkmcnt(5)
	v_add_f32_e32 v216, v216, v118
	s_waitcnt lgkmcnt(4)
	v_add_f32_e32 v217, v217, v119
	s_waitcnt lgkmcnt(3)
	v_add_f32_e32 v218, v218, v120
	s_waitcnt lgkmcnt(2)
	v_add_f32_e32 v219, v219, v121
	s_waitcnt lgkmcnt(1)
	v_add_f32_e32 v220, v220, v122
	s_waitcnt lgkmcnt(0)
	v_add_f32_e32 v221, v221, v123
	ds_bpermute_b32 v116, v205, v214
	ds_bpermute_b32 v117, v205, v215
	ds_bpermute_b32 v118, v205, v216
	ds_bpermute_b32 v119, v205, v217
	ds_bpermute_b32 v120, v205, v218
	ds_bpermute_b32 v121, v205, v219
	ds_bpermute_b32 v122, v205, v220
	ds_bpermute_b32 v123, v205, v221
	s_waitcnt lgkmcnt(7)
	v_add_f32_e32 v214, v214, v116
	s_waitcnt lgkmcnt(6)
	v_add_f32_e32 v215, v215, v117
	s_waitcnt lgkmcnt(5)
	v_add_f32_e32 v216, v216, v118
	s_waitcnt lgkmcnt(4)
	v_add_f32_e32 v217, v217, v119
	s_waitcnt lgkmcnt(3)
	v_add_f32_e32 v218, v218, v120
	s_waitcnt lgkmcnt(2)
	v_add_f32_e32 v219, v219, v121
	s_waitcnt lgkmcnt(1)
	v_add_f32_e32 v220, v220, v122
	s_waitcnt lgkmcnt(0)
	v_add_f32_e32 v221, v221, v123
	ds_bpermute_b32 v124, v200, v222
	ds_bpermute_b32 v125, v200, v223
	ds_bpermute_b32 v126, v200, v224
	ds_bpermute_b32 v127, v200, v225
	ds_bpermute_b32 v128, v200, v226
	ds_bpermute_b32 v129, v200, v227
	ds_bpermute_b32 v130, v200, v228
	ds_bpermute_b32 v131, v200, v229
	s_waitcnt lgkmcnt(7)
	v_add_f32_e32 v222, v222, v124
	s_waitcnt lgkmcnt(6)
	v_add_f32_e32 v223, v223, v125
	s_waitcnt lgkmcnt(5)
	v_add_f32_e32 v224, v224, v126
	s_waitcnt lgkmcnt(4)
	v_add_f32_e32 v225, v225, v127
	s_waitcnt lgkmcnt(3)
	v_add_f32_e32 v226, v226, v128
	s_waitcnt lgkmcnt(2)
	v_add_f32_e32 v227, v227, v129
	s_waitcnt lgkmcnt(1)
	v_add_f32_e32 v228, v228, v130
	s_waitcnt lgkmcnt(0)
	v_add_f32_e32 v229, v229, v131
	ds_bpermute_b32 v124, v201, v222
	ds_bpermute_b32 v125, v201, v223
	ds_bpermute_b32 v126, v201, v224
	ds_bpermute_b32 v127, v201, v225
	ds_bpermute_b32 v128, v201, v226
	ds_bpermute_b32 v129, v201, v227
	ds_bpermute_b32 v130, v201, v228
	ds_bpermute_b32 v131, v201, v229
	s_waitcnt lgkmcnt(7)
	v_add_f32_e32 v222, v222, v124
	s_waitcnt lgkmcnt(6)
	v_add_f32_e32 v223, v223, v125
	s_waitcnt lgkmcnt(5)
	v_add_f32_e32 v224, v224, v126
	s_waitcnt lgkmcnt(4)
	v_add_f32_e32 v225, v225, v127
	s_waitcnt lgkmcnt(3)
	v_add_f32_e32 v226, v226, v128
	s_waitcnt lgkmcnt(2)
	v_add_f32_e32 v227, v227, v129
	s_waitcnt lgkmcnt(1)
	v_add_f32_e32 v228, v228, v130
	s_waitcnt lgkmcnt(0)
	v_add_f32_e32 v229, v229, v131
	ds_bpermute_b32 v124, v202, v222
	ds_bpermute_b32 v125, v202, v223
	ds_bpermute_b32 v126, v202, v224
	ds_bpermute_b32 v127, v202, v225
	ds_bpermute_b32 v128, v202, v226
	ds_bpermute_b32 v129, v202, v227
	ds_bpermute_b32 v130, v202, v228
	ds_bpermute_b32 v131, v202, v229
	s_waitcnt lgkmcnt(7)
	v_add_f32_e32 v222, v222, v124
	s_waitcnt lgkmcnt(6)
	v_add_f32_e32 v223, v223, v125
	s_waitcnt lgkmcnt(5)
	v_add_f32_e32 v224, v224, v126
	s_waitcnt lgkmcnt(4)
	v_add_f32_e32 v225, v225, v127
	s_waitcnt lgkmcnt(3)
	v_add_f32_e32 v226, v226, v128
	s_waitcnt lgkmcnt(2)
	v_add_f32_e32 v227, v227, v129
	s_waitcnt lgkmcnt(1)
	v_add_f32_e32 v228, v228, v130
	s_waitcnt lgkmcnt(0)
	v_add_f32_e32 v229, v229, v131
	ds_bpermute_b32 v124, v203, v222
	ds_bpermute_b32 v125, v203, v223
	ds_bpermute_b32 v126, v203, v224
	ds_bpermute_b32 v127, v203, v225
	ds_bpermute_b32 v128, v203, v226
	ds_bpermute_b32 v129, v203, v227
	ds_bpermute_b32 v130, v203, v228
	ds_bpermute_b32 v131, v203, v229
	s_waitcnt lgkmcnt(7)
	v_add_f32_e32 v222, v222, v124
	s_waitcnt lgkmcnt(6)
	v_add_f32_e32 v223, v223, v125
	s_waitcnt lgkmcnt(5)
	v_add_f32_e32 v224, v224, v126
	s_waitcnt lgkmcnt(4)
	v_add_f32_e32 v225, v225, v127
	s_waitcnt lgkmcnt(3)
	v_add_f32_e32 v226, v226, v128
	s_waitcnt lgkmcnt(2)
	v_add_f32_e32 v227, v227, v129
	s_waitcnt lgkmcnt(1)
	v_add_f32_e32 v228, v228, v130
	s_waitcnt lgkmcnt(0)
	v_add_f32_e32 v229, v229, v131
	ds_bpermute_b32 v124, v204, v222
	ds_bpermute_b32 v125, v204, v223
	ds_bpermute_b32 v126, v204, v224
	ds_bpermute_b32 v127, v204, v225
	ds_bpermute_b32 v128, v204, v226
	ds_bpermute_b32 v129, v204, v227
	ds_bpermute_b32 v130, v204, v228
	ds_bpermute_b32 v131, v204, v229
	s_waitcnt lgkmcnt(7)
	v_add_f32_e32 v222, v222, v124
	s_waitcnt lgkmcnt(6)
	v_add_f32_e32 v223, v223, v125
	s_waitcnt lgkmcnt(5)
	v_add_f32_e32 v224, v224, v126
	s_waitcnt lgkmcnt(4)
	v_add_f32_e32 v225, v225, v127
	s_waitcnt lgkmcnt(3)
	v_add_f32_e32 v226, v226, v128
	s_waitcnt lgkmcnt(2)
	v_add_f32_e32 v227, v227, v129
	s_waitcnt lgkmcnt(1)
	v_add_f32_e32 v228, v228, v130
	s_waitcnt lgkmcnt(0)
	v_add_f32_e32 v229, v229, v131
	ds_bpermute_b32 v124, v205, v222
	ds_bpermute_b32 v125, v205, v223
	ds_bpermute_b32 v126, v205, v224
	ds_bpermute_b32 v127, v205, v225
	ds_bpermute_b32 v128, v205, v226
	ds_bpermute_b32 v129, v205, v227
	ds_bpermute_b32 v130, v205, v228
	ds_bpermute_b32 v131, v205, v229
	s_waitcnt lgkmcnt(7)
	v_add_f32_e32 v222, v222, v124
	s_waitcnt lgkmcnt(6)
	v_add_f32_e32 v223, v223, v125
	s_waitcnt lgkmcnt(5)
	v_add_f32_e32 v224, v224, v126
	s_waitcnt lgkmcnt(4)
	v_add_f32_e32 v225, v225, v127
	s_waitcnt lgkmcnt(3)
	v_add_f32_e32 v226, v226, v128
	s_waitcnt lgkmcnt(2)
	v_add_f32_e32 v227, v227, v129
	s_waitcnt lgkmcnt(1)
	v_add_f32_e32 v228, v228, v130
	s_waitcnt lgkmcnt(0)
	v_add_f32_e32 v229, v229, v131
	s_waitcnt vmcnt(0)
	s_and_saveexec_b64 s[44:45], s[10:11]
	v_fma_f32 v91, v58, v230, v214
	s_or_b64 exec, exec, s[44:45]
	s_and_saveexec_b64 s[44:45], s[12:13]
	v_fma_f32 v91, v59, v230, v215
	s_or_b64 exec, exec, s[44:45]
	s_and_saveexec_b64 s[44:45], s[14:15]
	v_fma_f32 v91, v56, v230, v216
	s_or_b64 exec, exec, s[44:45]
	s_and_saveexec_b64 s[44:45], s[16:17]
	v_fma_f32 v91, v57, v230, v217
	s_or_b64 exec, exec, s[44:45]
	s_and_saveexec_b64 s[44:45], s[18:19]
	v_fma_f32 v91, v54, v230, v218
	s_or_b64 exec, exec, s[44:45]
	s_and_saveexec_b64 s[44:45], s[20:21]
	v_fma_f32 v91, v55, v230, v219
	s_or_b64 exec, exec, s[44:45]
	s_and_saveexec_b64 s[44:45], s[22:23]
	v_fma_f32 v91, v52, v230, v220
	s_or_b64 exec, exec, s[44:45]
	s_and_saveexec_b64 s[44:45], s[24:25]
	v_fma_f32 v91, v53, v230, v221
	s_or_b64 exec, exec, s[44:45]
	s_and_saveexec_b64 s[44:45], s[26:27]
	v_fma_f32 v91, v50, v230, v222
	s_or_b64 exec, exec, s[44:45]
	s_and_saveexec_b64 s[44:45], s[28:29]
	v_fma_f32 v91, v51, v230, v223
	s_or_b64 exec, exec, s[44:45]
	s_and_saveexec_b64 s[44:45], s[30:31]
	v_fma_f32 v91, v48, v230, v224
	s_or_b64 exec, exec, s[44:45]
	s_and_saveexec_b64 s[44:45], s[34:35]
	v_fma_f32 v91, v49, v230, v225
	s_or_b64 exec, exec, s[44:45]
	s_and_saveexec_b64 s[44:45], s[36:37]
	v_fma_f32 v91, v46, v230, v226
	s_or_b64 exec, exec, s[44:45]
	s_and_saveexec_b64 s[44:45], s[38:39]
	v_fma_f32 v91, v47, v230, v227
	s_or_b64 exec, exec, s[44:45]
	s_and_saveexec_b64 s[44:45], s[40:41]
	v_fma_f32 v91, v44, v230, v228
	s_or_b64 exec, exec, s[44:45]
	s_and_saveexec_b64 s[44:45], s[42:43]
	v_fma_f32 v91, v45, v230, v229
	s_or_b64 exec, exec, s[44:45]
	s_and_saveexec_b64 s[44:45], vcc
	s_cbranch_execz .LBB11_790
	v_mul_f32_e32 v44, 0x3d922279, v91
	v_fmaak_f32 v44, v91, v44, 0x3fcc422a
	v_mul_f32_e32 v44, v91, v44
	v_mul_f32_e32 v44, 0xbfb8aa3b, v44
	v_exp_f32_e32 v44, v44
	s_nop 0
	v_add_f32_e32 v44, 1.0, v44
	v_rcp_f32_e32 v44, v44
	s_nop 0
	v_mul_f32_e32 v44, v91, v44
	s_waitcnt lgkmcnt(0)
	v_cvt_pk_bf16_f32 v46, v44, v1
	v_lshl_add_u64 v[44:45], s[88:89], 0, v[42:43]
	global_store_short v[44:45], v46, off sc1
	s_branch .LBB11_790

.LBB11_845:
	s_or_b64 exec, exec, s[14:15]
	v_cmp_eq_u32_e32 vcc, 1, v0
	s_waitcnt vmcnt(0)
	v_readfirstlane_b32 s0, v4
	s_cbranch_vccnz .LBB11_883
	v_cvt_f32_u32_e32 v4, v2
	v_sub_u32_e32 v5, 0, v2
	v_add_u32_e32 v3, s0, v3
	v_rcp_iflag_f32_e32 v4, v4
	s_nop 0
	v_mul_f32_e32 v4, 0x4f7ffffe, v4
	v_cvt_u32_f32_e32 v4, v4
	v_mul_lo_u32 v5, v5, v4
	v_mul_hi_u32 v5, v4, v5
	v_add_u32_e32 v4, v4, v5
	v_mul_hi_u32 v4, v3, v4
	v_mul_lo_u32 v5, v4, v2
	v_sub_u32_e32 v5, v3, v5
	v_add_u32_e32 v6, 1, v4
	v_cmp_ge_u32_e32 vcc, v5, v2
	v_add_u32_e32 v3, 1, v3
	s_nop 0
	v_cndmask_b32_e32 v4, v4, v6, vcc
	v_sub_u32_e32 v6, v5, v2
	v_cndmask_b32_e32 v5, v5, v6, vcc
	v_add_u32_e32 v6, 1, v4
	v_cmp_ge_u32_e32 vcc, v5, v2
	s_nop 1
	v_cndmask_b32_e32 v4, v4, v6, vcc
	v_mul_lo_u32 v4, v2, v4
	v_add_u32_e32 v2, v4, v2
	v_cmp_eq_u32_e32 vcc, v3, v2
	s_and_saveexec_b64 s[12:13], vcc
	s_cbranch_execz .LBB11_882
	s_mov_b64 s[14:15], exec
	s_nop 0
	s_waitcnt lgkmcnt(0)
	s_waitcnt vmcnt(0)
	v_mbcnt_lo_u32_b32 v2, s14, 0
	v_mbcnt_hi_u32_b32 v2, s15, v2
	v_cmp_eq_u32_e32 vcc, 0, v2
	s_and_saveexec_b64 s[16:17], vcc
	s_cbranch_execz .LBB11_849
	s_bcnt1_i32_b64 s0, s[14:15]
	v_mov_b32_e32 v3, s0
	v_readlane_b32 s0, v247, 36
	v_readlane_b32 s1, v247, 37
	s_nop 4
	global_atomic_add v3, v1, v3, s[0:1] sc0

.LBB11_1059:
	s_or_b64 exec, exec, s[30:31]
	s_waitcnt lgkmcnt(0)
	s_waitcnt lgkmcnt(0)
	s_barrier
	ds_read_b128 v[108:111], v106
	ds_read_b128 v[112:115], v106 offset:33024
	v_readlane_b32 s0, v245, 5
	s_andn2_b64 vcc, exec, s[2:3]
	s_waitcnt vmcnt(7) lgkmcnt(1)
	v_mfma_f32_16x16x32_bf16 v[108:111], v[108:111], v[62:65], 0
	v_add_u32_e32 v0, s0, v86
	s_waitcnt lgkmcnt(0)
	v_mfma_f32_16x16x32_bf16 v[62:65], v[112:115], v[62:65], 0
	ds_read_b128 v[112:115], v106 offset:64
	s_waitcnt vmcnt(6) lgkmcnt(0)
	v_mfma_f32_16x16x32_bf16 v[108:111], v[112:115], v[58:61], v[108:111]
	ds_read_b128 v[112:115], v106 offset:33088
	s_waitcnt lgkmcnt(0)
	v_mfma_f32_16x16x32_bf16 v[58:61], v[112:115], v[58:61], v[62:65]
	s_nop 2
	ds_read_b128 v[62:65], v106 offset:128
	s_waitcnt vmcnt(5) lgkmcnt(0)
	v_mfma_f32_16x16x32_bf16 v[62:65], v[62:65], v[54:57], v[108:111]
	s_nop 2
	ds_read_b128 v[108:111], v106 offset:33152
	s_waitcnt lgkmcnt(0)
	v_mfma_f32_16x16x32_bf16 v[54:57], v[108:111], v[54:57], v[58:61]
	s_nop 2
	ds_read_b128 v[58:61], v106 offset:192
	s_waitcnt vmcnt(4) lgkmcnt(0)
	v_mfma_f32_16x16x32_bf16 v[58:61], v[58:61], v[50:53], v[62:65]
	s_nop 2
	ds_read_b128 v[62:65], v106 offset:33216
	s_waitcnt lgkmcnt(0)
	v_mfma_f32_16x16x32_bf16 v[50:53], v[62:65], v[50:53], v[54:57]
	s_nop 2
	ds_read_b128 v[54:57], v106 offset:256
	s_waitcnt vmcnt(3) lgkmcnt(0)
	v_mfma_f32_16x16x32_bf16 v[54:57], v[54:57], v[46:49], v[58:61]
	s_nop 2
	ds_read_b128 v[58:61], v106 offset:33280
	s_waitcnt lgkmcnt(0)
	v_mfma_f32_16x16x32_bf16 v[46:49], v[58:61], v[46:49], v[50:53]
	s_nop 2
	ds_read_b128 v[50:53], v106 offset:320
	s_waitcnt vmcnt(2) lgkmcnt(0)
	v_mfma_f32_16x16x32_bf16 v[50:53], v[50:53], v[42:45], v[54:57]
	s_nop 2
	ds_read_b128 v[54:57], v106 offset:33344
	s_waitcnt lgkmcnt(0)
	v_mfma_f32_16x16x32_bf16 v[42:45], v[54:57], v[42:45], v[46:49]
	s_nop 2
	ds_read_b128 v[46:49], v106 offset:384
	s_waitcnt vmcnt(1) lgkmcnt(0)
	v_mfma_f32_16x16x32_bf16 v[46:49], v[46:49], v[38:41], v[50:53]
	s_nop 2
	ds_read_b128 v[50:53], v106 offset:33408
	s_waitcnt lgkmcnt(0)
	v_mfma_f32_16x16x32_bf16 v[42:45], v[50:53], v[38:41], v[42:45]
	ds_read_b128 v[38:41], v106 offset:448
	s_waitcnt vmcnt(0) lgkmcnt(0)
	v_mfma_f32_16x16x32_bf16 v[38:41], v[38:41], v[34:37], v[46:49]
	s_nop 2
	ds_read_b128 v[46:49], v106 offset:33472
	s_waitcnt lgkmcnt(0)
	v_mfma_f32_16x16x32_bf16 v[34:37], v[46:49], v[34:37], v[42:45]
	s_nop 1
	ds_write_b128 v0, v[38:41]
	s_nop 4
	ds_write_b128 v0, v[34:37] offset:1024
	s_waitcnt lgkmcnt(0)
	s_waitcnt lgkmcnt(0)
	s_barrier
	s_cbranch_vccnz .LBB11_1026
	v_readlane_b32 s0, v245, 6
	s_nop 1
	v_add_u32_e32 v0, s0, v86
	ds_read_b128 v[42:45], v0 offset:4096
	s_lshl_b32 s0, s9, 17
	s_waitcnt lgkmcnt(0)
	v_pk_add_f32 v[44:45], v[40:41], v[44:45]
	v_pk_add_f32 v[42:43], v[38:39], v[42:43]
	ds_read_b128 v[38:41], v0 offset:5120
	s_waitcnt lgkmcnt(0)
	v_pk_add_f32 v[40:41], v[36:37], v[40:41]
	v_pk_add_f32 v[38:39], v[34:35], v[38:39]
	ds_read_b128 v[34:37], v0 offset:8192
	s_waitcnt lgkmcnt(0)
	v_pk_add_f32 v[44:45], v[44:45], v[36:37]
	v_pk_add_f32 v[42:43], v[42:43], v[34:35]
	ds_read_b128 v[34:37], v0 offset:9216
	s_waitcnt lgkmcnt(0)
	v_pk_add_f32 v[40:41], v[40:41], v[36:37]
	v_pk_add_f32 v[46:47], v[38:39], v[34:35]
	ds_read_b128 v[36:39], v0 offset:12288
	s_waitcnt lgkmcnt(0)
	v_pk_add_f32 v[34:35], v[44:45], v[38:39]
	v_pk_add_f32 v[42:43], v[42:43], v[36:37]
	ds_read_b128 v[36:39], v0 offset:13312
	v_subrev_u32_e32 v0, s0, v97
	s_waitcnt lgkmcnt(0)
	v_pk_add_f32 v[44:45], v[46:47], v[36:37]
	v_add_u32_e32 v36, s34, v87
	v_pk_add_f32 v[40:41], v[40:41], v[38:39]
	v_ashrrev_i32_e32 v37, 31, v36
	v_lshlrev_b64 v[38:39], 1, v[0:1]
	v_lshl_add_u64 v[46:47], s[66:67], 0, v[38:39]
	v_lshlrev_b64 v[48:49], 1, v[36:37]
	v_lshl_add_u64 v[36:37], v[46:47], 0, v[48:49]
	v_lshl_add_u64 v[38:39], s[64:65], 0, v[38:39]
	v_lshl_add_u64 v[38:39], v[38:39], 0, v[48:49]
	global_load_dwordx2 v[46:47], v[36:37], off
	global_load_dwordx2 v[48:49], v[38:39], off
	v_mul_f32_e32 v0, 0xbfb8aa3b, v44
	v_exp_f32_e32 v0, v0
	s_waitcnt vmcnt(1)
	v_lshlrev_b32_e32 v50, 16, v46
	v_add_f32_e32 v0, 1.0, v0
	v_rcp_f32_e32 v44, v0
	v_mul_f32_e32 v0, 0xbfb8aa3b, v45
	v_exp_f32_e32 v0, v0
	v_and_b32_e32 v51, 0xffff0000, v46
	s_waitcnt vmcnt(0)
	v_lshlrev_b32_e32 v52, 16, v48
	v_and_b32_e32 v53, 0xffff0000, v48
	v_add_f32_e32 v0, 1.0, v0
	v_rcp_f32_e32 v45, v0
	v_mul_f32_e32 v0, 0xbfb8aa3b, v40
	v_exp_f32_e32 v0, v0
	v_pk_add_f32 v[50:51], v[50:51], v[52:53]
	v_lshlrev_b32_e32 v46, 16, v49
	v_pk_fma_f32 v[42:43], v[42:43], v[44:45], v[50:51]
	v_add_f32_e32 v0, 1.0, v0
	v_rcp_f32_e32 v40, v0
	v_mul_f32_e32 v0, 0xbfb8aa3b, v41
	v_exp_f32_e32 v0, v0
	v_lshlrev_b32_e32 v44, 16, v47
	v_and_b32_e32 v45, 0xffff0000, v47
	v_and_b32_e32 v47, 0xffff0000, v49
	v_add_f32_e32 v0, 1.0, v0
	v_rcp_f32_e32 v41, v0
	v_pk_add_f32 v[44:45], v[44:45], v[46:47]
	s_nop 0
	v_pk_fma_f32 v[34:35], v[34:35], v[40:41], v[44:45]
	v_cvt_pk_bf16_f32 v40, v42, v43
	s_nop 0
	v_cvt_pk_bf16_f32 v41, v34, v35
	v_lshlrev_b32_e32 v44, 16, v40
	v_and_b32_e32 v45, 0xffff0000, v40
	v_lshlrev_b32_e32 v46, 16, v41
	v_and_b32_e32 v47, 0xffff0000, v41
	v_sub_f32_e32 v0, v34, v46
	v_sub_f32_e32 v35, v35, v47
	v_sub_f32_e32 v34, v42, v44
	v_sub_f32_e32 v42, v43, v45
	v_cvt_pk_bf16_f32 v34, v34, v42
	v_cvt_pk_bf16_f32 v35, v0, v35
	global_store_dwordx2 v[36:37], v[40:41], off sc1
	global_store_dwordx2 v[38:39], v[34:35], off sc1
	v_lshlrev_b32_e32 v42, 16, v34
	v_and_b32_e32 v43, 0xffff0000, v34
	v_lshlrev_b32_e32 v48, 16, v35
	v_and_b32_e32 v49, 0xffff0000, v35
	v_pk_add_f32 v[46:47], v[46:47], v[48:49]
	v_pk_add_f32 v[42:43], v[44:45], v[42:43]
	v_mul_f32_e32 v34, v47, v47
	v_mul_f32_e32 v0, v43, v43
	v_fmac_f32_e32 v0, v42, v42
	v_fmac_f32_e32 v34, v46, v46
	v_add_f32_e32 v0, v0, v34
	ds_bpermute_b32 v34, v204, v0
	s_waitcnt lgkmcnt(0)
	v_add_f32_e32 v34, v0, v34
	ds_bpermute_b32 v35, v205, v34
	s_and_saveexec_b64 s[30:31], s[10:11]
	s_cbranch_execz .LBB11_1025
	v_add_u32_e32 v0, 0x4000, v84
	v_lshl_add_u64 v[36:37], v[0:1], 2, s[28:29]
	s_waitcnt lgkmcnt(0)
	v_add_f32_e32 v0, v34, v35
	global_atomic_add_f32 v[36:37], v0, off
	s_branch .LBB11_1025

.LBB11_1339:
	s_or_b64 exec, exec, s[38:39]
	s_waitcnt lgkmcnt(0)
	s_waitcnt lgkmcnt(0)
	s_barrier
	ds_read_b128 v[140:143], v139
	ds_read_b128 v[144:147], v139 offset:33024
	v_readlane_b32 s0, v245, 5
	s_waitcnt vmcnt(15) lgkmcnt(1)
	v_mfma_f32_16x16x32_bf16 v[140:143], v[140:143], v[94:97], 0
	v_add_u32_e32 v0, s0, v120
	v_readlane_b32 s0, v245, 17
	v_readlane_b32 s1, v245, 18
	s_waitcnt lgkmcnt(0)
	v_mfma_f32_16x16x32_bf16 v[94:97], v[144:147], v[94:97], 0
	ds_read_b128 v[144:147], v139 offset:64
	s_andn2_b64 vcc, exec, s[0:1]
	s_waitcnt vmcnt(14) lgkmcnt(0)
	v_mfma_f32_16x16x32_bf16 v[140:143], v[144:147], v[90:93], v[140:143]
	ds_read_b128 v[144:147], v139 offset:33088
	s_waitcnt lgkmcnt(0)
	v_mfma_f32_16x16x32_bf16 v[90:93], v[144:147], v[90:93], v[94:97]
	s_nop 2
	ds_read_b128 v[94:97], v139 offset:128
	s_waitcnt vmcnt(13) lgkmcnt(0)
	v_mfma_f32_16x16x32_bf16 v[94:97], v[94:97], v[86:89], v[140:143]
	s_nop 2
	ds_read_b128 v[140:143], v139 offset:33152
	s_waitcnt lgkmcnt(0)
	v_mfma_f32_16x16x32_bf16 v[86:89], v[140:143], v[86:89], v[90:93]
	s_nop 2
	ds_read_b128 v[90:93], v139 offset:192
	s_waitcnt vmcnt(12) lgkmcnt(0)
	v_mfma_f32_16x16x32_bf16 v[90:93], v[90:93], v[82:85], v[94:97]
	s_nop 2
	ds_read_b128 v[94:97], v139 offset:33216
	s_waitcnt lgkmcnt(0)
	v_mfma_f32_16x16x32_bf16 v[82:85], v[94:97], v[82:85], v[86:89]
	s_nop 2
	ds_read_b128 v[86:89], v139 offset:256
	s_waitcnt vmcnt(11) lgkmcnt(0)
	v_mfma_f32_16x16x32_bf16 v[86:89], v[86:89], v[78:81], v[90:93]
	s_nop 2
	ds_read_b128 v[90:93], v139 offset:33280
	s_waitcnt lgkmcnt(0)
	v_mfma_f32_16x16x32_bf16 v[78:81], v[90:93], v[78:81], v[82:85]
	s_nop 2
	ds_read_b128 v[82:85], v139 offset:320
	s_waitcnt vmcnt(10) lgkmcnt(0)
	v_mfma_f32_16x16x32_bf16 v[82:85], v[82:85], v[74:77], v[86:89]
	s_nop 2
	ds_read_b128 v[86:89], v139 offset:33344
	s_waitcnt lgkmcnt(0)
	v_mfma_f32_16x16x32_bf16 v[74:77], v[86:89], v[74:77], v[78:81]
	s_nop 2
	ds_read_b128 v[78:81], v139 offset:384
	s_waitcnt vmcnt(9) lgkmcnt(0)
	v_mfma_f32_16x16x32_bf16 v[78:81], v[78:81], v[70:73], v[82:85]
	s_nop 2
	ds_read_b128 v[82:85], v139 offset:33408
	s_waitcnt lgkmcnt(0)
	v_mfma_f32_16x16x32_bf16 v[70:73], v[82:85], v[70:73], v[74:77]
	s_nop 2
	ds_read_b128 v[74:77], v139 offset:448
	s_waitcnt vmcnt(8) lgkmcnt(0)
	v_mfma_f32_16x16x32_bf16 v[74:77], v[74:77], v[66:69], v[78:81]
	s_nop 2
	ds_read_b128 v[78:81], v139 offset:33472
	s_waitcnt lgkmcnt(0)
	v_mfma_f32_16x16x32_bf16 v[66:69], v[78:81], v[66:69], v[70:73]
	s_nop 2
	ds_read_b128 v[70:73], v139 offset:512
	s_waitcnt vmcnt(7) lgkmcnt(0)
	v_mfma_f32_16x16x32_bf16 v[70:73], v[70:73], v[62:65], v[74:77]
	s_nop 2
	ds_read_b128 v[74:77], v139 offset:33536
	s_waitcnt lgkmcnt(0)
	v_mfma_f32_16x16x32_bf16 v[62:65], v[74:77], v[62:65], v[66:69]
	s_nop 2
	ds_read_b128 v[66:69], v139 offset:576
	s_waitcnt vmcnt(6) lgkmcnt(0)
	v_mfma_f32_16x16x32_bf16 v[66:69], v[66:69], v[58:61], v[70:73]
	s_nop 2
	ds_read_b128 v[70:73], v139 offset:33600
	s_waitcnt lgkmcnt(0)
	v_mfma_f32_16x16x32_bf16 v[58:61], v[70:73], v[58:61], v[62:65]
	s_nop 2
	ds_read_b128 v[62:65], v139 offset:640
	s_waitcnt vmcnt(5) lgkmcnt(0)
	v_mfma_f32_16x16x32_bf16 v[62:65], v[62:65], v[54:57], v[66:69]
	s_nop 2
	ds_read_b128 v[66:69], v139 offset:33664
	s_waitcnt lgkmcnt(0)
	v_mfma_f32_16x16x32_bf16 v[54:57], v[66:69], v[54:57], v[58:61]
	s_nop 2
	ds_read_b128 v[58:61], v139 offset:704
	s_waitcnt vmcnt(4) lgkmcnt(0)
	v_mfma_f32_16x16x32_bf16 v[58:61], v[58:61], v[50:53], v[62:65]
	s_nop 2
	ds_read_b128 v[62:65], v139 offset:33728
	s_waitcnt lgkmcnt(0)
	v_mfma_f32_16x16x32_bf16 v[50:53], v[62:65], v[50:53], v[54:57]
	s_nop 2
	ds_read_b128 v[54:57], v139 offset:768
	s_waitcnt vmcnt(3) lgkmcnt(0)
	v_mfma_f32_16x16x32_bf16 v[54:57], v[54:57], v[46:49], v[58:61]
	s_nop 2
	ds_read_b128 v[58:61], v139 offset:33792
	s_waitcnt lgkmcnt(0)
	v_mfma_f32_16x16x32_bf16 v[46:49], v[58:61], v[46:49], v[50:53]
	s_nop 2
	ds_read_b128 v[50:53], v139 offset:832
	s_waitcnt vmcnt(2) lgkmcnt(0)
	v_mfma_f32_16x16x32_bf16 v[50:53], v[50:53], v[42:45], v[54:57]
	s_nop 2
	ds_read_b128 v[54:57], v139 offset:33856
	s_waitcnt lgkmcnt(0)
	v_mfma_f32_16x16x32_bf16 v[42:45], v[54:57], v[42:45], v[46:49]
	s_nop 2
	ds_read_b128 v[46:49], v139 offset:896
	s_waitcnt vmcnt(1) lgkmcnt(0)
	v_mfma_f32_16x16x32_bf16 v[46:49], v[46:49], v[38:41], v[50:53]
	s_nop 2
	ds_read_b128 v[50:53], v139 offset:33920
	s_waitcnt lgkmcnt(0)
	v_mfma_f32_16x16x32_bf16 v[42:45], v[50:53], v[38:41], v[42:45]
	ds_read_b128 v[38:41], v139 offset:960
	s_waitcnt vmcnt(0) lgkmcnt(0)
	v_mfma_f32_16x16x32_bf16 v[38:41], v[38:41], v[34:37], v[46:49]
	s_nop 2
	ds_read_b128 v[46:49], v139 offset:33984
	s_waitcnt lgkmcnt(0)
	v_mfma_f32_16x16x32_bf16 v[34:37], v[46:49], v[34:37], v[42:45]
	s_nop 1
	ds_write_b128 v0, v[38:41]
	s_nop 4
	ds_write_b128 v0, v[34:37] offset:1024
	s_waitcnt lgkmcnt(0)
	s_waitcnt lgkmcnt(0)
	s_barrier
	s_cbranch_vccnz .LBB11_1306
	v_add_u32_e32 v0, 0x4000, v118
	v_lshl_add_u64 v[42:43], v[0:1], 2, s[30:31]
	global_load_dword v52, v[42:43], off
	v_readlane_b32 s0, v245, 19
	v_lshlrev_b64 v[50:51], 13, v[0:1]
	s_ashr_i32 s37, s36, 31
	v_add_u32_e32 v46, s0, v120
	ds_read_b128 v[42:45], v46 offset:8192
	ds_read_b128 v[46:49], v46 offset:9216
	v_lshl_add_u64 v[50:51], s[62:63], 0, v[50:51]
	v_lshl_add_u64 v[50:51], s[36:37], 1, v[50:51]
	v_lshl_add_u64 v[50:51], v[100:101], 1, v[50:51]
	s_waitcnt lgkmcnt(1)
	v_pk_add_f32 v[40:41], v[40:41], v[44:45]
	v_pk_add_f32 v[38:39], v[38:39], v[42:43]
	s_waitcnt lgkmcnt(0)
	v_pk_add_f32 v[36:37], v[36:37], v[48:49]
	v_pk_add_f32 v[34:35], v[34:35], v[46:47]
	s_cmpk_lt_i32 s6, 0x80
	s_waitcnt vmcnt(0)
	v_fmamk_f32 v0, v52, 0x3a800000, v206
	v_mul_f32_e32 v44, 0x4b800000, v0
	v_cmp_gt_f32_e32 vcc, s77, v0
	s_nop 1
	v_cndmask_b32_e32 v0, v0, v44, vcc
	v_rsq_f32_e32 v0, v0
	s_nop 0
	v_mul_f32_e32 v42, 0x45800000, v0
	v_cndmask_b32_e32 v0, v0, v42, vcc
	v_mul_f32_e32 v38, v38, v0
	v_mul_f32_e32 v39, v39, v0
	v_mul_f32_e32 v40, v40, v0
	v_mul_f32_e32 v41, v41, v0
	v_mul_f32_e32 v42, v34, v0
	v_mul_f32_e32 v43, v35, v0
	v_mul_f32_e32 v44, v36, v0
	v_mul_f32_e32 v0, v37, v0
	v_mul_f32_e32 v34, 0x3d922279, v38
	v_mul_f32_e32 v35, 0x3d922279, v39
	v_mul_f32_e32 v36, 0x3d922279, v40
	v_mul_f32_e32 v37, 0x3d922279, v41
	v_mul_f32_e32 v45, 0x3d922279, v42
	v_mul_f32_e32 v46, 0x3d922279, v43
	v_mul_f32_e32 v47, 0x3d922279, v44
	v_mul_f32_e32 v48, 0x3d922279, v0
	v_fmaak_f32 v34, v38, v34, 0x3fcc422a
	v_fmaak_f32 v35, v39, v35, 0x3fcc422a
	v_fmaak_f32 v36, v40, v36, 0x3fcc422a
	v_fmaak_f32 v37, v41, v37, 0x3fcc422a
	v_fmaak_f32 v45, v42, v45, 0x3fcc422a
	v_fmaak_f32 v46, v43, v46, 0x3fcc422a
	v_fmaak_f32 v47, v44, v47, 0x3fcc422a
	v_fmaak_f32 v48, v0, v48, 0x3fcc422a
	v_mul_f32_e32 v34, v38, v34
	v_mul_f32_e32 v35, v39, v35
	v_mul_f32_e32 v36, v40, v36
	v_mul_f32_e32 v37, v41, v37
	v_mul_f32_e32 v45, v42, v45
	v_mul_f32_e32 v46, v43, v46
	v_mul_f32_e32 v47, v44, v47
	v_mul_f32_e32 v48, v0, v48
	v_mul_f32_e32 v34, 0xbfb8aa3b, v34
	v_mul_f32_e32 v35, 0xbfb8aa3b, v35
	v_mul_f32_e32 v36, 0xbfb8aa3b, v36
	v_mul_f32_e32 v37, 0xbfb8aa3b, v37
	v_mul_f32_e32 v45, 0xbfb8aa3b, v45
	v_mul_f32_e32 v46, 0xbfb8aa3b, v46
	v_mul_f32_e32 v47, 0xbfb8aa3b, v47
	v_mul_f32_e32 v48, 0xbfb8aa3b, v48
	v_exp_f32_e32 v34, v34
	v_exp_f32_e32 v35, v35
	v_exp_f32_e32 v36, v36
	v_exp_f32_e32 v37, v37
	v_exp_f32_e32 v45, v45
	v_exp_f32_e32 v46, v46
	v_exp_f32_e32 v47, v47
	v_exp_f32_e32 v48, v48
	v_add_f32_e32 v34, 1.0, v34
	v_add_f32_e32 v35, 1.0, v35
	v_add_f32_e32 v36, 1.0, v36
	v_add_f32_e32 v37, 1.0, v37
	v_add_f32_e32 v45, 1.0, v45
	v_add_f32_e32 v46, 1.0, v46
	v_add_f32_e32 v47, 1.0, v47
	v_add_f32_e32 v48, 1.0, v48
	v_rcp_f32_e32 v34, v34
	v_rcp_f32_e32 v35, v35
	v_rcp_f32_e32 v36, v36
	v_rcp_f32_e32 v37, v37
	v_rcp_f32_e32 v45, v45
	v_rcp_f32_e32 v46, v46
	v_rcp_f32_e32 v47, v47
	v_rcp_f32_e32 v48, v48
	v_mul_f32_e32 v34, v38, v34
	v_mul_f32_e32 v35, v39, v35
	v_mul_f32_e32 v36, v40, v36
	v_mul_f32_e32 v37, v41, v37
	v_mul_f32_e32 v38, v42, v45
	v_mul_f32_e32 v39, v43, v46
	v_mul_f32_e32 v40, v44, v47
	v_mul_f32_e32 v0, v0, v48
	v_cvt_pk_bf16_f32 v42, v34, v35
	v_cvt_pk_bf16_f32 v43, v36, v37
	global_store_dwordx2 v[50:51], v[42:43], off sc1
	v_cvt_pk_bf16_f32 v42, v38, v39
	v_cvt_pk_bf16_f32 v43, v40, v0
	global_store_dwordx2 v[50:51], v[42:43], off offset:32 sc1
	s_cbranch_scc1 .LBB11_1306
	v_mul_f32_e32 v41, v35, v35
	v_fmac_f32_e32 v41, v34, v34
	v_add_f32_e32 v34, 0, v34
	v_add_f32_e32 v34, v35, v34
	v_fmac_f32_e32 v41, v36, v36
	v_add_f32_e32 v34, v36, v34
	v_fmac_f32_e32 v41, v37, v37
	v_add_f32_e32 v34, v37, v34
	v_fmac_f32_e32 v41, v38, v38
	v_add_f32_e32 v34, v38, v34
	v_fmac_f32_e32 v41, v39, v39
	v_add_f32_e32 v34, v39, v34
	v_fmac_f32_e32 v41, v40, v40
	v_add_f32_e32 v34, v40, v34
	v_add_f32_e32 v34, v0, v34
	v_fmac_f32_e32 v41, v0, v0
	ds_bpermute_b32 v35, v204, v34
	ds_bpermute_b32 v0, v204, v41
	s_waitcnt lgkmcnt(1)
	v_add_f32_e32 v34, v34, v35
	s_waitcnt lgkmcnt(0)
	v_add_f32_e32 v36, v41, v0
	ds_bpermute_b32 v35, v205, v34
	ds_bpermute_b32 v37, v205, v36
	s_and_saveexec_b64 s[36:37], s[12:13]
	s_cbranch_execz .LBB11_1305
	s_lshl_b32 s0, s9, 8
	v_subrev_u32_e32 v0, s0, v130
	v_lshl_add_u64 v[38:39], v[0:1], 2, s[34:35]
	s_waitcnt lgkmcnt(1)
	v_add_f32_e32 v0, v34, v35
	s_waitcnt lgkmcnt(0)
	v_add_f32_e32 v34, v36, v37
	global_atomic_add_f32 v[38:39], v0, off
	global_atomic_add_f32 v[38:39], v34, off offset:4
	s_branch .LBB11_1305

.LBB11_1363:
	s_or_b64 exec, exec, s[16:17]
	v_cmp_eq_u32_e32 vcc, 1, v0
	s_waitcnt vmcnt(0)
	v_readfirstlane_b32 s0, v4
	s_cbranch_vccnz .LBB11_1401
	v_cvt_f32_u32_e32 v4, v2
	v_sub_u32_e32 v5, 0, v2
	v_add_u32_e32 v3, s0, v3
	v_rcp_iflag_f32_e32 v4, v4
	s_nop 0
	v_mul_f32_e32 v4, 0x4f7ffffe, v4
	v_cvt_u32_f32_e32 v4, v4
	v_mul_lo_u32 v5, v5, v4
	v_mul_hi_u32 v5, v4, v5
	v_add_u32_e32 v4, v4, v5
	v_mul_hi_u32 v4, v3, v4
	v_mul_lo_u32 v5, v4, v2
	v_sub_u32_e32 v5, v3, v5
	v_add_u32_e32 v6, 1, v4
	v_cmp_ge_u32_e32 vcc, v5, v2
	v_add_u32_e32 v3, 1, v3
	s_nop 0
	v_cndmask_b32_e32 v4, v4, v6, vcc
	v_sub_u32_e32 v6, v5, v2
	v_cndmask_b32_e32 v5, v5, v6, vcc
	v_add_u32_e32 v6, 1, v4
	v_cmp_ge_u32_e32 vcc, v5, v2
	s_nop 1
	v_cndmask_b32_e32 v4, v4, v6, vcc
	v_mul_lo_u32 v4, v2, v4
	v_add_u32_e32 v2, v4, v2
	v_cmp_eq_u32_e32 vcc, v3, v2
	s_and_saveexec_b64 s[14:15], vcc
	s_cbranch_execz .LBB11_1400
	s_mov_b64 s[16:17], exec
	s_nop 0
	s_waitcnt lgkmcnt(0)
	s_waitcnt vmcnt(0)
	v_mbcnt_lo_u32_b32 v2, s16, 0
	v_mbcnt_hi_u32_b32 v2, s17, v2
	v_cmp_eq_u32_e32 vcc, 0, v2
	s_and_saveexec_b64 s[18:19], vcc
	s_cbranch_execz .LBB11_1367
	s_bcnt1_i32_b64 s0, s[16:17]
	v_mov_b32_e32 v3, s0
	v_readlane_b32 s0, v247, 36
	v_readlane_b32 s1, v247, 37
	s_nop 4
	global_atomic_add v3, v1, v3, s[0:1] sc0

.LBB11_1526:
	s_or_b64 exec, exec, s[10:11]
	v_readlane_b32 s0, v245, 25
	v_readlane_b32 s10, v248, 14
	v_readlane_b32 s1, v245, 26
	v_readlane_b32 s11, v248, 15
	v_mov_b32_e32 v0, v199
	v_mov_b32_e32 v2, v198
	s_andn2_b64 vcc, exec, s[0:1]
	s_barrier
	s_cbranch_vccnz .LBB11_1528
	s_load_dwordx8 s[12:19], s[10:11], 0x68
	s_load_dwordx4 s[20:23], s[10:11], 0x130
	s_lshl_b32 s60, s94, 10
	s_lshl_b64 s[0:1], s[60:61], 2
	v_lshlrev_b32_e32 v4, 2, v0
	s_waitcnt lgkmcnt(0)
	s_add_u32 s0, s18, s0
	s_addc_u32 s1, s19, s1
	s_lshl_b32 s60, s94, 11
	s_lshl_b64 s[6:7], s[60:61], 2
	s_add_u32 s8, s14, s6
	s_addc_u32 s9, s15, s7
	s_add_u32 s6, s12, s6
	s_addc_u32 s7, s13, s7
	s_add_u32 s12, s22, s44
	s_addc_u32 s13, s23, s43
	v_readlane_b32 s10, v245, 28
	v_readlane_b32 s11, v245, 29
	s_add_u32 s10, s22, s10
	v_ashrrev_i32_e32 v5, 31, v4
	s_addc_u32 s11, s23, s11
	v_lshlrev_b64 v[2:3], 1, v[4:5]
	v_lshl_add_u64 v[12:13], s[10:11], 0, v[2:3]
	s_mov_b32 s10, 0x1b401000
	v_add_co_u32_e32 v6, vcc, s10, v12
	v_readlane_b32 s10, v242, 24
	v_readlane_b32 s11, v242, 25
	s_add_u32 s10, s12, s10
	s_addc_u32 s11, s13, s11
	v_addc_co_u32_e32 v7, vcc, 0, v13, vcc
	global_load_dwordx2 v[16:17], v[6:7], off
	s_nop 0
	global_load_dwordx2 v[14:15], v211, s[10:11]
	v_lshlrev_b64 v[18:19], 2, v[4:5]
	v_lshl_add_u64 v[4:5], s[8:9], 0, v[18:19]
	v_lshl_add_u64 v[8:9], s[6:7], 0, v[18:19]
	global_load_dwordx4 v[4:7], v[4:5], off
	v_ashrrev_i32_e32 v20, 6, v0
	global_load_dwordx4 v[8:11], v[8:9], off
	v_lshlrev_b32_e32 v22, 7, v20
	v_ashrrev_i32_e32 v23, 31, v22
	v_lshl_add_u64 v[22:23], v[22:23], 2, s[0:1]
	s_mov_b32 s0, 0x1b400000
	v_add_co_u32_e32 v12, vcc, s0, v12
	s_lshl_b64 s[0:1], s[94:95], 20
	s_add_u32 s0, s20, s0
	s_addc_u32 s1, s21, s1
	v_readlane_b32 s6, v245, 27
	s_add_u32 s0, s0, s6
	s_addc_u32 s1, s1, 0
	s_lshl_b64 s[6:7], s[94:95], 19
	v_ashrrev_i32_e32 v21, 31, v20
	v_addc_co_u32_e32 v13, vcc, 0, v13, vcc
	v_lshl_add_u64 v[18:19], s[0:1], 0, v[18:19]
	s_add_u32 s0, s16, s6
	s_mov_b32 s1, 0x8900000
	v_lshlrev_b64 v[20:21], 16, v[20:21]
	v_add_co_u32_e32 v18, vcc, s1, v18
	s_addc_u32 s1, s17, s7
	v_lshl_add_u64 v[20:21], s[0:1], 0, v[20:21]
	s_mov_b32 s0, 0x3a000000
	v_addc_co_u32_e32 v19, vcc, 0, v19, vcc
	global_load_dwordx2 v[12:13], v[12:13], off
	s_waitcnt vmcnt(4)
	v_lshlrev_b32_e32 v24, 16, v16
	s_waitcnt vmcnt(3)
	v_pk_mul_f32 v[14:15], v[14:15], s[0:1] op_sel_hi:[1,0]
	v_readlane_b32 s0, v245, 30
	v_fma_f32 v0, -v14, v14, v15
	v_max_f32_e32 v0, 0, v0
	v_add_f32_e32 v0, 0x358637bd, v0
	v_cmp_gt_f32_e32 vcc, s77, v0
	v_mul_f32_e32 v25, 0x4b800000, v0
	v_and_b32_e32 v15, 0xffff0000, v16
	v_cndmask_b32_e32 v0, v0, v25, vcc
	v_rsq_f32_e32 v0, v0
	v_lshlrev_b32_e32 v16, 16, v17
	v_and_b32_e32 v17, 0xffff0000, v17
	v_sub_f32_e32 v17, v17, v14
	v_sub_f32_e32 v16, v16, v14
	v_sub_f32_e32 v15, v15, v14
	v_sub_f32_e32 v14, v24, v14
	v_mul_f32_e32 v24, 0x45800000, v0
	v_cndmask_b32_e32 v0, v0, v24, vcc
	v_pk_mul_f32 v[14:15], v[14:15], v[0:1] op_sel_hi:[1,0]
	v_pk_mul_f32 v[16:17], v[16:17], v[0:1] op_sel_hi:[1,0]
	s_waitcnt vmcnt(1)
	v_pk_fma_f32 v[4:5], v[8:9], v[14:15], v[4:5]
	v_pk_fma_f32 v[6:7], v[10:11], v[16:17], v[6:7]
	global_store_dwordx4 v[18:19], v[4:7], off sc1
	global_load_dword v0, v[20:21], off
	global_load_dword v8, v[22:23], off
	v_readlane_b32 s1, v245, 31
	s_add_u32 s0, s22, s0
	s_addc_u32 s1, s23, s1
	v_lshl_add_u64 v[2:3], s[0:1], 0, v[2:3]
	v_add_co_u32_e32 v2, vcc, 0x23600000, v2
	s_waitcnt vmcnt(3)
	v_lshlrev_b32_e32 v10, 16, v12
	v_and_b32_e32 v11, 0xffff0000, v12
	v_lshlrev_b32_e32 v12, 16, v13
	v_and_b32_e32 v13, 0xffff0000, v13
	v_addc_co_u32_e32 v3, vcc, 0, v3, vcc
	s_waitcnt vmcnt(0)
	v_pk_fma_f32 v[4:5], v[0:1], v[4:5], v[8:9] op_sel_hi:[0,1,0]
	v_pk_fma_f32 v[6:7], v[0:1], v[6:7], v[8:9] op_sel_hi:[0,1,0]
	v_pk_mul_f32 v[4:5], v[4:5], v[10:11]
	v_pk_mul_f32 v[6:7], v[6:7], v[12:13]
	v_cvt_pk_bf16_f32 v4, v4, v5
	s_nop 0
	v_cvt_pk_bf16_f32 v5, v6, v7
	global_store_dwordx2 v[2:3], v[4:5], off sc1

.LBB11_1762:
	s_or_b64 exec, exec, s[30:31]
	s_waitcnt lgkmcnt(0)
	s_waitcnt lgkmcnt(0)
	s_barrier
	ds_read_b128 v[140:143], v138
	v_readlane_b32 s0, v243, 0
	s_andn2_b64 vcc, exec, s[2:3]
	s_waitcnt vmcnt(15) lgkmcnt(0)
	v_mfma_f32_16x16x32_bf16 v[94:97], v[140:143], v[94:97], 0
	ds_read_b128 v[140:143], v138 offset:64
	v_add_u32_e32 v0, s0, v118
	s_waitcnt vmcnt(14) lgkmcnt(0)
	v_mfma_f32_16x16x32_bf16 v[90:93], v[140:143], v[90:93], v[94:97]
	s_nop 3
	ds_read_b128 v[94:97], v138 offset:128
	s_waitcnt vmcnt(13) lgkmcnt(0)
	v_mfma_f32_16x16x32_bf16 v[86:89], v[94:97], v[86:89], v[90:93]
	s_nop 2
	ds_read_b128 v[90:93], v138 offset:192
	s_waitcnt vmcnt(12) lgkmcnt(0)
	v_mfma_f32_16x16x32_bf16 v[82:85], v[90:93], v[82:85], v[86:89]
	s_nop 2
	ds_read_b128 v[86:89], v138 offset:256
	s_waitcnt vmcnt(11) lgkmcnt(0)
	v_mfma_f32_16x16x32_bf16 v[78:81], v[86:89], v[78:81], v[82:85]
	s_nop 2
	ds_read_b128 v[82:85], v138 offset:320
	s_waitcnt vmcnt(10) lgkmcnt(0)
	v_mfma_f32_16x16x32_bf16 v[74:77], v[82:85], v[74:77], v[78:81]
	s_nop 2
	ds_read_b128 v[78:81], v138 offset:384
	s_waitcnt vmcnt(9) lgkmcnt(0)
	v_mfma_f32_16x16x32_bf16 v[70:73], v[78:81], v[70:73], v[74:77]
	s_nop 2
	ds_read_b128 v[74:77], v138 offset:448
	s_waitcnt vmcnt(8) lgkmcnt(0)
	v_mfma_f32_16x16x32_bf16 v[66:69], v[74:77], v[66:69], v[70:73]
	s_nop 2
	ds_read_b128 v[70:73], v138 offset:512
	s_waitcnt vmcnt(7) lgkmcnt(0)
	v_mfma_f32_16x16x32_bf16 v[62:65], v[70:73], v[62:65], v[66:69]
	s_nop 2
	ds_read_b128 v[66:69], v138 offset:576
	s_waitcnt vmcnt(6) lgkmcnt(0)
	v_mfma_f32_16x16x32_bf16 v[58:61], v[66:69], v[58:61], v[62:65]
	s_nop 2
	ds_read_b128 v[62:65], v138 offset:640
	s_waitcnt vmcnt(5) lgkmcnt(0)
	v_mfma_f32_16x16x32_bf16 v[54:57], v[62:65], v[54:57], v[58:61]
	s_nop 2
	ds_read_b128 v[58:61], v138 offset:704
	s_waitcnt vmcnt(4) lgkmcnt(0)
	v_mfma_f32_16x16x32_bf16 v[50:53], v[58:61], v[50:53], v[54:57]
	s_nop 2
	ds_read_b128 v[54:57], v138 offset:768
	s_waitcnt vmcnt(3) lgkmcnt(0)
	v_mfma_f32_16x16x32_bf16 v[46:49], v[54:57], v[46:49], v[50:53]
	s_nop 2
	ds_read_b128 v[50:53], v138 offset:832
	s_waitcnt vmcnt(2) lgkmcnt(0)
	v_mfma_f32_16x16x32_bf16 v[42:45], v[50:53], v[42:45], v[46:49]
	s_nop 2
	ds_read_b128 v[46:49], v138 offset:896
	s_waitcnt vmcnt(1) lgkmcnt(0)
	v_mfma_f32_16x16x32_bf16 v[38:41], v[46:49], v[38:41], v[42:45]
	s_nop 2
	ds_read_b128 v[42:45], v138 offset:960
	s_waitcnt vmcnt(0) lgkmcnt(0)
	v_mfma_f32_16x16x32_bf16 v[34:37], v[42:45], v[34:37], v[38:41]
	s_nop 7
	ds_write_b128 v0, v[34:37]
	s_waitcnt lgkmcnt(0)
	s_waitcnt lgkmcnt(0)
	s_barrier
	s_cbranch_vccnz .LBB11_1729
	v_readlane_b32 s0, v245, 40
	s_nop 1
	v_add_u32_e32 v0, s0, v118
	ds_read_b128 v[38:41], v0 offset:2048
	s_lshl_b32 s0, s9, 17
	s_waitcnt lgkmcnt(0)
	v_pk_add_f32 v[40:41], v[36:37], v[40:41]
	v_pk_add_f32 v[38:39], v[34:35], v[38:39]
	ds_read_b128 v[34:37], v0 offset:4096
	s_waitcnt lgkmcnt(0)
	v_pk_add_f32 v[40:41], v[40:41], v[36:37]
	v_pk_add_f32 v[38:39], v[38:39], v[34:35]
	ds_read_b128 v[34:37], v0 offset:6144
	v_subrev_u32_e32 v0, s0, v129
	s_waitcnt lgkmcnt(0)
	v_pk_add_f32 v[34:35], v[38:39], v[34:35]
	v_add_u32_e32 v38, s34, v119
	v_pk_add_f32 v[36:37], v[40:41], v[36:37]
	v_ashrrev_i32_e32 v39, 31, v38
	v_lshlrev_b64 v[40:41], 1, v[0:1]
	v_lshl_add_u64 v[42:43], s[66:67], 0, v[40:41]
	v_lshlrev_b64 v[38:39], 1, v[38:39]
	v_lshl_add_u64 v[42:43], v[42:43], 0, v[38:39]
	v_lshl_add_u64 v[40:41], s[64:65], 0, v[40:41]
	v_lshl_add_u64 v[38:39], v[40:41], 0, v[38:39]
	global_load_dwordx2 v[40:41], v[42:43], off
	global_load_dwordx2 v[44:45], v[38:39], off
	s_waitcnt vmcnt(1)
	v_lshlrev_b32_e32 v46, 16, v40
	v_and_b32_e32 v47, 0xffff0000, v40
	s_waitcnt vmcnt(0)
	v_lshlrev_b32_e32 v48, 16, v44
	v_and_b32_e32 v49, 0xffff0000, v44
	v_lshlrev_b32_e32 v40, 16, v41
	v_and_b32_e32 v41, 0xffff0000, v41
	v_lshlrev_b32_e32 v44, 16, v45
	v_and_b32_e32 v45, 0xffff0000, v45
	v_pk_add_f32 v[46:47], v[46:47], v[48:49]
	v_pk_add_f32 v[40:41], v[40:41], v[44:45]
	v_pk_add_f32 v[34:35], v[34:35], v[46:47]
	v_pk_add_f32 v[36:37], v[36:37], v[40:41]
	v_cvt_pk_bf16_f32 v40, v34, v35
	s_nop 0
	v_cvt_pk_bf16_f32 v41, v36, v37
	v_lshlrev_b32_e32 v44, 16, v40
	v_and_b32_e32 v45, 0xffff0000, v40
	v_lshlrev_b32_e32 v46, 16, v41
	v_and_b32_e32 v47, 0xffff0000, v41
	v_sub_f32_e32 v0, v36, v46
	v_sub_f32_e32 v36, v37, v47
	v_sub_f32_e32 v34, v34, v44
	v_sub_f32_e32 v35, v35, v45
	v_cvt_pk_bf16_f32 v34, v34, v35
	v_cvt_pk_bf16_f32 v35, v0, v36
	global_store_dwordx2 v[42:43], v[40:41], off sc1
	global_store_dwordx2 v[38:39], v[34:35], off sc1
	v_lshlrev_b32_e32 v36, 16, v34
	v_and_b32_e32 v37, 0xffff0000, v34
	v_lshlrev_b32_e32 v48, 16, v35
	v_and_b32_e32 v49, 0xffff0000, v35
	v_pk_add_f32 v[46:47], v[46:47], v[48:49]
	v_pk_add_f32 v[36:37], v[44:45], v[36:37]
	v_mul_f32_e32 v34, v47, v47
	v_mul_f32_e32 v0, v37, v37
	v_fmac_f32_e32 v0, v36, v36
	v_fmac_f32_e32 v34, v46, v46
	v_add_f32_e32 v0, v0, v34
	ds_bpermute_b32 v34, v204, v0
	s_waitcnt lgkmcnt(0)
	v_add_f32_e32 v34, v0, v34
	ds_bpermute_b32 v35, v205, v34
	s_and_saveexec_b64 s[30:31], s[10:11]
	s_cbranch_execz .LBB11_1728
	v_add_u32_e32 v0, 0x4000, v116
	v_lshl_add_u64 v[36:37], v[0:1], 2, s[28:29]
	s_waitcnt lgkmcnt(0)
	v_add_f32_e32 v0, v34, v35
	global_atomic_add_f32 v[36:37], v0, off
	s_branch .LBB11_1728

.LBB11_1946:
	s_or_b64 exec, exec, s[10:11]
	s_waitcnt lgkmcnt(0)
	s_waitcnt lgkmcnt(0)
	s_barrier
	ds_read_b128 v[108:111], v106
	ds_read_b128 v[112:115], v106 offset:33024
	v_readlane_b32 s0, v245, 5
	s_andn2_b64 vcc, exec, s[2:3]
	s_waitcnt vmcnt(7) lgkmcnt(1)
	v_mfma_f32_16x16x32_bf16 v[108:111], v[108:111], v[62:65], 0
	v_add_u32_e32 v0, s0, v88
	s_waitcnt lgkmcnt(0)
	v_mfma_f32_16x16x32_bf16 v[62:65], v[112:115], v[62:65], 0
	ds_read_b128 v[112:115], v106 offset:64
	s_waitcnt vmcnt(6) lgkmcnt(0)
	v_mfma_f32_16x16x32_bf16 v[108:111], v[112:115], v[58:61], v[108:111]
	ds_read_b128 v[112:115], v106 offset:33088
	s_waitcnt lgkmcnt(0)
	v_mfma_f32_16x16x32_bf16 v[58:61], v[112:115], v[58:61], v[62:65]
	s_nop 2
	ds_read_b128 v[62:65], v106 offset:128
	s_waitcnt vmcnt(5) lgkmcnt(0)
	v_mfma_f32_16x16x32_bf16 v[62:65], v[62:65], v[54:57], v[108:111]
	s_nop 2
	ds_read_b128 v[108:111], v106 offset:33152
	s_waitcnt lgkmcnt(0)
	v_mfma_f32_16x16x32_bf16 v[54:57], v[108:111], v[54:57], v[58:61]
	s_nop 2
	ds_read_b128 v[58:61], v106 offset:192
	s_waitcnt vmcnt(4) lgkmcnt(0)
	v_mfma_f32_16x16x32_bf16 v[58:61], v[58:61], v[50:53], v[62:65]
	s_nop 2
	ds_read_b128 v[62:65], v106 offset:33216
	s_waitcnt lgkmcnt(0)
	v_mfma_f32_16x16x32_bf16 v[50:53], v[62:65], v[50:53], v[54:57]
	s_nop 2
	ds_read_b128 v[54:57], v106 offset:256
	s_waitcnt vmcnt(3) lgkmcnt(0)
	v_mfma_f32_16x16x32_bf16 v[54:57], v[54:57], v[46:49], v[58:61]
	s_nop 2
	ds_read_b128 v[58:61], v106 offset:33280
	s_waitcnt lgkmcnt(0)
	v_mfma_f32_16x16x32_bf16 v[46:49], v[58:61], v[46:49], v[50:53]
	s_nop 2
	ds_read_b128 v[50:53], v106 offset:320
	s_waitcnt vmcnt(2) lgkmcnt(0)
	v_mfma_f32_16x16x32_bf16 v[50:53], v[50:53], v[42:45], v[54:57]
	s_nop 2
	ds_read_b128 v[54:57], v106 offset:33344
	s_waitcnt lgkmcnt(0)
	v_mfma_f32_16x16x32_bf16 v[42:45], v[54:57], v[42:45], v[46:49]
	s_nop 2
	ds_read_b128 v[46:49], v106 offset:384
	s_waitcnt vmcnt(1) lgkmcnt(0)
	v_mfma_f32_16x16x32_bf16 v[46:49], v[46:49], v[38:41], v[50:53]
	s_nop 2
	ds_read_b128 v[50:53], v106 offset:33408
	s_waitcnt lgkmcnt(0)
	v_mfma_f32_16x16x32_bf16 v[42:45], v[50:53], v[38:41], v[42:45]
	ds_read_b128 v[38:41], v106 offset:448
	s_waitcnt vmcnt(0) lgkmcnt(0)
	v_mfma_f32_16x16x32_bf16 v[38:41], v[38:41], v[34:37], v[46:49]
	s_nop 2
	ds_read_b128 v[46:49], v106 offset:33472
	s_waitcnt lgkmcnt(0)
	v_mfma_f32_16x16x32_bf16 v[34:37], v[46:49], v[34:37], v[42:45]
	s_nop 1
	ds_write_b128 v0, v[38:41]
	s_nop 4
	ds_write_b128 v0, v[34:37] offset:1024
	s_waitcnt lgkmcnt(0)
	s_waitcnt lgkmcnt(0)
	s_barrier
	s_cbranch_vccnz .LBB11_1913
	v_readlane_b32 s0, v245, 6
	s_ashr_i32 s35, s34, 31
	s_nop 0
	v_add_u32_e32 v0, s0, v88
	ds_read_b128 v[42:45], v0 offset:4096
	s_waitcnt lgkmcnt(0)
	v_pk_add_f32 v[44:45], v[40:41], v[44:45]
	v_pk_add_f32 v[42:43], v[38:39], v[42:43]
	ds_read_b128 v[38:41], v0 offset:5120
	s_waitcnt lgkmcnt(0)
	v_pk_add_f32 v[40:41], v[36:37], v[40:41]
	v_pk_add_f32 v[38:39], v[34:35], v[38:39]
	ds_read_b128 v[34:37], v0 offset:8192
	s_waitcnt lgkmcnt(0)
	v_pk_add_f32 v[44:45], v[44:45], v[36:37]
	v_pk_add_f32 v[42:43], v[42:43], v[34:35]
	ds_read_b128 v[34:37], v0 offset:9216
	s_waitcnt lgkmcnt(0)
	v_pk_add_f32 v[40:41], v[40:41], v[36:37]
	v_pk_add_f32 v[46:47], v[38:39], v[34:35]
	ds_read_b128 v[34:37], v0 offset:12288
	s_waitcnt lgkmcnt(0)
	v_pk_add_f32 v[44:45], v[44:45], v[36:37]
	ds_read_b128 v[36:39], v0 offset:13312
	v_add_u32_e32 v0, 0x4000, v86
	v_pk_add_f32 v[42:43], v[42:43], v[34:35]
	s_waitcnt lgkmcnt(0)
	v_pk_add_f32 v[34:35], v[40:41], v[38:39]
	v_lshl_add_u64 v[38:39], v[0:1], 2, s[30:31]
	global_load_dword v38, v[38:39], off
	v_pk_add_f32 v[36:37], v[46:47], v[36:37]
	s_waitcnt vmcnt(0)
	v_fmamk_f32 v38, v38, 0x3a800000, v206
	v_cmp_gt_f32_e32 vcc, s77, v38
	v_mul_f32_e32 v39, 0x4b800000, v38
	s_nop 0
	v_cndmask_b32_e32 v38, v38, v39, vcc
	v_rsq_f32_e32 v38, v38
	s_nop 0
	v_mul_f32_e32 v39, 0x45800000, v38
	v_cndmask_b32_e32 v38, v38, v39, vcc
	v_mul_f32_e32 v46, 0x3d800000, v38
	v_lshlrev_b64 v[38:39], 11, v[0:1]
	v_mul_f32_e32 v0, v42, v46
	v_mul_f32_e32 v40, v43, v46
	v_lshl_add_u64 v[38:39], s[78:79], 0, v[38:39]
	v_cvt_pk_bf16_f32 v40, v0, v40
	v_mul_f32_e32 v0, v44, v46
	v_mul_f32_e32 v41, v45, v46
	v_lshl_add_u64 v[38:39], s[34:35], 1, v[38:39]
	v_cvt_pk_bf16_f32 v41, v0, v41
	v_lshl_add_u64 v[38:39], v[68:69], 1, v[38:39]
	v_mul_f32_e32 v0, v36, v46
	v_mul_f32_e32 v36, v37, v46
	global_store_dwordx2 v[38:39], v[40:41], off sc1
	v_cvt_pk_bf16_f32 v36, v0, v36
	v_mul_f32_e32 v0, v34, v46
	v_mul_f32_e32 v34, v35, v46
	v_cvt_pk_bf16_f32 v37, v0, v34
	global_store_dwordx2 v[38:39], v[36:37], off offset:32 sc1
	s_branch .LBB11_1913

.LBB11_1966:
	s_or_b64 exec, exec, s[14:15]
	v_cmp_eq_u32_e32 vcc, 1, v0
	s_waitcnt vmcnt(0)
	v_readfirstlane_b32 s0, v4
	s_cbranch_vccnz .LBB11_2003
	v_cvt_f32_u32_e32 v4, v2
	v_sub_u32_e32 v5, 0, v2
	v_add_u32_e32 v3, s0, v3
	v_rcp_iflag_f32_e32 v4, v4
	s_nop 0
	v_mul_f32_e32 v4, 0x4f7ffffe, v4
	v_cvt_u32_f32_e32 v4, v4
	v_mul_lo_u32 v5, v5, v4
	v_mul_hi_u32 v5, v4, v5
	v_add_u32_e32 v4, v4, v5
	v_mul_hi_u32 v4, v3, v4
	v_mul_lo_u32 v5, v4, v2
	v_sub_u32_e32 v5, v3, v5
	v_add_u32_e32 v6, 1, v4
	v_cmp_ge_u32_e32 vcc, v5, v2
	v_add_u32_e32 v3, 1, v3
	s_nop 0
	v_cndmask_b32_e32 v4, v4, v6, vcc
	v_sub_u32_e32 v6, v5, v2
	v_cndmask_b32_e32 v5, v5, v6, vcc
	v_add_u32_e32 v6, 1, v4
	v_cmp_ge_u32_e32 vcc, v5, v2
	s_nop 1
	v_cndmask_b32_e32 v4, v4, v6, vcc
	v_mul_lo_u32 v4, v2, v4
	v_add_u32_e32 v2, v4, v2
	v_cmp_eq_u32_e32 vcc, v3, v2
	s_and_b64 exec, exec, vcc
	s_cbranch_execz .LBB11_2003
	s_mov_b64 s[10:11], exec
	s_nop 0
	s_waitcnt lgkmcnt(0)
	s_waitcnt vmcnt(0)
	v_mbcnt_lo_u32_b32 v2, s10, 0
	v_mbcnt_hi_u32_b32 v2, s11, v2
	v_cmp_eq_u32_e32 vcc, 0, v2
	s_and_saveexec_b64 s[14:15], vcc
	s_cbranch_execz .LBB11_1970
	s_bcnt1_i32_b64 s0, s[10:11]
	v_mov_b32_e32 v3, s0
	v_readlane_b32 s0, v247, 36
	v_readlane_b32 s1, v247, 37
	s_nop 4
	global_atomic_add v3, v1, v3, s[0:1] sc0

.LBB11_2225:
	s_add_u32 s0, s58, s90
	s_addc_u32 s1, s59, s91
	s_lshl_b32 s10, s68, 2
	s_add_u32 s0, s0, s10
	s_addc_u32 s1, s1, 0
	v_lshl_add_u64 v[66:67], v[100:101], 2, s[0:1]
	v_readlane_b32 s0, v243, 2
	v_readlane_b32 s1, v243, 3
	v_mov_b32_e32 v105, s84
	s_waitcnt lgkmcnt(0)
	v_lshl_add_u64 v[2:3], v[66:67], 0, s[0:1]
	v_readlane_b32 s0, v244, 4
	v_readlane_b32 s1, v244, 5
	s_nop 1
	v_lshl_add_u64 v[4:5], v[66:67], 0, s[0:1]
	v_readlane_b32 s0, v244, 6
	v_readlane_b32 s1, v244, 7
	global_load_dwordx4 v[62:65], v[2:3], off nt
	global_load_dwordx4 v[42:45], v[4:5], off nt
	v_lshl_add_u64 v[2:3], v[66:67], 0, s[0:1]
	v_readlane_b32 s0, v244, 8
	v_readlane_b32 s1, v244, 9
	s_nop 1
	v_lshl_add_u64 v[4:5], v[66:67], 0, s[0:1]
	v_readlane_b32 s0, v244, 10
	v_readlane_b32 s1, v244, 11
	global_load_dwordx4 v[58:61], v[2:3], off nt
	global_load_dwordx4 v[34:37], v[4:5], off nt
	v_lshl_add_u64 v[2:3], v[66:67], 0, s[0:1]
	v_readlane_b32 s0, v244, 12
	v_readlane_b32 s1, v244, 13
	s_nop 1
	v_lshl_add_u64 v[4:5], v[66:67], 0, s[0:1]
	v_readlane_b32 s0, v244, 14
	v_readlane_b32 s1, v244, 15
	global_load_dwordx4 v[54:57], v[2:3], off nt
	global_load_dwordx4 v[26:29], v[4:5], off nt
	v_lshl_add_u64 v[2:3], v[66:67], 0, s[0:1]
	v_readlane_b32 s0, v244, 16
	v_readlane_b32 s1, v244, 17
	s_nop 1
	v_lshl_add_u64 v[4:5], v[66:67], 0, s[0:1]
	v_readlane_b32 s0, v244, 18
	v_readlane_b32 s1, v244, 19
	global_load_dwordx4 v[50:53], v[2:3], off nt
	global_load_dwordx4 v[22:25], v[4:5], off nt
	v_lshl_add_u64 v[2:3], v[66:67], 0, s[0:1]
	v_readlane_b32 s0, v244, 20
	v_readlane_b32 s1, v244, 21
	s_nop 1
	v_lshl_add_u64 v[4:5], v[66:67], 0, s[0:1]
	v_readlane_b32 s0, v244, 22
	v_readlane_b32 s1, v244, 23
	global_load_dwordx4 v[46:49], v[2:3], off nt
	global_load_dwordx4 v[18:21], v[4:5], off nt
	v_lshl_add_u64 v[2:3], v[66:67], 0, s[0:1]
	v_readlane_b32 s0, v244, 24
	v_readlane_b32 s1, v244, 25
	s_nop 1
	v_lshl_add_u64 v[4:5], v[66:67], 0, s[0:1]
	v_readlane_b32 s0, v244, 26
	v_readlane_b32 s1, v244, 27
	global_load_dwordx4 v[38:41], v[2:3], off nt
	global_load_dwordx4 v[14:17], v[4:5], off nt
	v_lshl_add_u64 v[2:3], v[66:67], 0, s[0:1]
	v_readlane_b32 s0, v244, 28
	v_readlane_b32 s1, v244, 29
	s_nop 1
	v_lshl_add_u64 v[4:5], v[66:67], 0, s[0:1]
	v_readlane_b32 s0, v244, 30
	v_readlane_b32 s1, v244, 31
	global_load_dwordx4 v[30:33], v[2:3], off nt
	global_load_dwordx4 v[10:13], v[4:5], off nt
	v_lshl_add_u64 v[2:3], v[66:67], 0, s[0:1]
	v_readlane_b32 s0, v244, 32
	v_readlane_b32 s1, v244, 33
	s_nop 1
	v_lshl_add_u64 v[4:5], v[66:67], 0, s[0:1]
	global_load_dwordx4 v[6:9], v[2:3], off nt
	s_nop 0
	global_load_dwordx4 v[2:5], v[4:5], off nt
	s_waitcnt lgkmcnt(0)
	s_barrier
	ds_read2st64_b32 v[68:69], v0 offset1:1
	ds_read2st64_b32 v[70:71], v0 offset0:2 offset1:3
	s_waitcnt lgkmcnt(1)
	v_max3_f32 v72, v68, s72, v69
	s_waitcnt lgkmcnt(0)
	v_max3_f32 v72, v72, v70, v71
	ds_bpermute_b32 v73, v200, v72
	s_waitcnt lgkmcnt(0)
	v_max_f32_e32 v73, v73, v73
	v_max_f32_e32 v72, v72, v73
	ds_bpermute_b32 v73, v201, v72
	s_waitcnt lgkmcnt(0)
	v_max_f32_e32 v73, v73, v73
	v_max_f32_e32 v72, v72, v73
	ds_bpermute_b32 v73, v202, v72
	s_waitcnt lgkmcnt(0)
	v_max_f32_e32 v73, v73, v73
	v_max_f32_e32 v72, v72, v73
	ds_bpermute_b32 v73, v203, v72
	s_waitcnt lgkmcnt(0)
	v_max_f32_e32 v73, v73, v73
	v_max_f32_e32 v72, v72, v73
	ds_bpermute_b32 v73, v204, v72
	s_waitcnt lgkmcnt(0)
	v_max_f32_e32 v73, v73, v73
	v_max_f32_e32 v72, v72, v73
	ds_bpermute_b32 v73, v205, v72
	s_waitcnt lgkmcnt(0)
	v_max_f32_e32 v73, v73, v73
	v_max_f32_e32 v104, v72, v73
	v_sub_f32_e32 v68, v68, v104
	v_mul_f32_e32 v68, 0x3fb8aa3b, v68
	v_sub_f32_e32 v69, v69, v104
	v_exp_f32_e32 v68, v68
	v_mul_f32_e32 v69, 0x3fb8aa3b, v69
	v_sub_f32_e32 v70, v70, v104
	v_exp_f32_e32 v69, v69
	v_mul_f32_e32 v70, 0x3fb8aa3b, v70
	v_sub_f32_e32 v71, v71, v104
	v_exp_f32_e32 v70, v70
	v_mul_f32_e32 v71, 0x3fb8aa3b, v71
	v_exp_f32_e32 v71, v71
	v_add_f32_e32 v68, 0, v68
	v_add_f32_e32 v68, v69, v68
	v_add_f32_e32 v68, v70, v68
	v_add_f32_e32 v68, v71, v68
	ds_bpermute_b32 v69, v200, v68
	s_waitcnt lgkmcnt(0)
	v_add_f32_e32 v68, v68, v69
	ds_bpermute_b32 v69, v201, v68
	s_waitcnt lgkmcnt(0)
	v_add_f32_e32 v68, v68, v69
	ds_bpermute_b32 v69, v202, v68
	s_waitcnt lgkmcnt(0)
	v_add_f32_e32 v68, v68, v69
	ds_bpermute_b32 v69, v203, v68
	s_waitcnt lgkmcnt(0)
	v_add_f32_e32 v76, v68, v69
	ds_bpermute_b32 v77, v204, v76
	ds_read_b128 v[68:71], v105
	ds_read_b128 v[72:75], v105 offset:16
	s_waitcnt lgkmcnt(2)
	v_add_f32_e32 v84, v76, v77
	ds_bpermute_b32 v85, v205, v84
	s_waitcnt lgkmcnt(2)
	v_sub_f32_e32 v68, v68, v104
	v_mul_f32_e32 v68, 0x3fb8aa3b, v68
	v_exp_f32_e32 v68, v68
	ds_read_b128 v[76:79], v105 offset:32
	ds_read_b128 v[80:83], v105 offset:48
	s_waitcnt lgkmcnt(2)
	v_add_f32_e32 v84, v84, v85
	v_div_scale_f32 v85, s[0:1], v84, v84, 1.0
	v_rcp_f32_e32 v86, v85
	v_div_scale_f32 v87, vcc, 1.0, v84, 1.0
	v_readlane_b32 s0, v244, 34
	v_fma_f32 v88, -v85, v86, 1.0
	v_fmac_f32_e32 v86, v88, v86
	v_mul_f32_e32 v88, v87, v86
	v_fma_f32 v89, -v85, v88, v87
	v_fmac_f32_e32 v88, v89, v86
	v_fma_f32 v85, -v85, v88, v87
	v_div_fmas_f32 v85, v85, v86, v88
	v_div_fixup_f32 v139, v85, v84, 1.0
	v_mul_f32_e32 v138, v68, v139
	v_sub_f32_e32 v68, v69, v104
	v_sub_f32_e32 v69, v70, v104
	v_mul_f32_e32 v68, 0x3fb8aa3b, v68
	v_mul_f32_e32 v69, 0x3fb8aa3b, v69
	v_sub_f32_e32 v70, v71, v104
	v_exp_f32_e32 v68, v68
	v_exp_f32_e32 v69, v69
	v_mul_f32_e32 v70, 0x3fb8aa3b, v70
	v_exp_f32_e32 v70, v70
	v_sub_f32_e32 v71, v72, v104
	v_mul_f32_e32 v71, 0x3fb8aa3b, v71
	v_mul_f32_e32 v140, v68, v139
	v_mul_f32_e32 v142, v69, v139
	v_sub_f32_e32 v68, v73, v104
	v_sub_f32_e32 v69, v74, v104
	v_exp_f32_e32 v71, v71
	v_mul_f32_e32 v144, v70, v139
	v_mul_f32_e32 v68, 0x3fb8aa3b, v68
	v_mul_f32_e32 v69, 0x3fb8aa3b, v69
	v_sub_f32_e32 v70, v75, v104
	v_exp_f32_e32 v68, v68
	v_exp_f32_e32 v69, v69
	v_mul_f32_e32 v70, 0x3fb8aa3b, v70
	v_exp_f32_e32 v70, v70
	v_mul_f32_e32 v146, v71, v139
	s_waitcnt lgkmcnt(1)
	v_sub_f32_e32 v71, v76, v104
	v_mul_f32_e32 v71, 0x3fb8aa3b, v71
	v_mul_f32_e32 v148, v68, v139
	v_mul_f32_e32 v150, v139, v69
	v_sub_f32_e32 v68, v77, v104
	v_sub_f32_e32 v69, v78, v104
	v_exp_f32_e32 v71, v71
	v_mul_f32_e32 v152, v139, v70
	v_mul_f32_e32 v68, 0x3fb8aa3b, v68
	v_mul_f32_e32 v69, 0x3fb8aa3b, v69
	v_sub_f32_e32 v70, v79, v104
	v_exp_f32_e32 v68, v68
	v_exp_f32_e32 v69, v69
	v_mul_f32_e32 v70, 0x3fb8aa3b, v70
	v_exp_f32_e32 v70, v70
	v_mul_f32_e32 v154, v139, v71
	s_waitcnt lgkmcnt(0)
	v_sub_f32_e32 v71, v80, v104
	v_readlane_b32 s1, v244, 35
	v_mul_f32_e32 v71, 0x3fb8aa3b, v71
	v_mul_f32_e32 v156, v139, v68
	v_mul_f32_e32 v158, v139, v69
	v_lshl_add_u64 v[68:69], v[66:67], 0, s[0:1]
	v_exp_f32_e32 v71, v71
	v_mul_f32_e32 v160, v139, v70
	v_sub_f32_e32 v70, v81, v104
	global_load_dwordx4 v[106:109], v[68:69], off nt
	v_mul_f32_e32 v68, 0x3fb8aa3b, v70
	v_exp_f32_e32 v70, v68
	v_sub_f32_e32 v68, v82, v104
	v_mul_f32_e32 v68, 0x3fb8aa3b, v68
	v_readlane_b32 s0, v244, 36
	v_mul_f32_e32 v162, v139, v71
	v_exp_f32_e32 v71, v68
	v_sub_f32_e32 v68, v83, v104
	v_readlane_b32 s1, v244, 37
	v_mul_f32_e32 v72, 0x3fb8aa3b, v68
	v_mul_f32_e32 v164, v139, v70
	v_lshl_add_u64 v[68:69], v[66:67], 0, s[0:1]
	v_readlane_b32 s0, v244, 38
	v_readlane_b32 s1, v244, 39
	global_load_dwordx4 v[110:113], v[68:69], off nt
	v_mul_f32_e32 v166, v139, v71
	v_lshl_add_u64 v[68:69], v[66:67], 0, s[0:1]
	global_load_dwordx4 v[114:117], v[68:69], off nt
	v_readlane_b32 s0, v244, 40
	v_readlane_b32 s1, v244, 41
	v_exp_f32_e32 v72, v72
	s_waitcnt vmcnt(18)
	v_pk_fma_f32 v[62:63], v[62:63], v[138:139], 0 op_sel_hi:[1,0,0]
	v_lshl_add_u64 v[68:69], v[66:67], 0, s[0:1]
	v_readlane_b32 s0, v244, 42
	v_readlane_b32 s1, v244, 43
	global_load_dwordx4 v[118:121], v[68:69], off nt
	v_mul_f32_e32 v168, v139, v72
	v_lshl_add_u64 v[68:69], v[66:67], 0, s[0:1]
	v_readlane_b32 s0, v244, 44
	v_readlane_b32 s1, v244, 45
	v_pk_fma_f32 v[64:65], v[64:65], v[138:139], 0 op_sel_hi:[1,0,0]
	s_waitcnt vmcnt(18)
	v_pk_fma_f32 v[42:43], v[42:43], v[140:141], v[62:63] op_sel_hi:[1,0,1]
	v_lshl_add_u64 v[70:71], v[66:67], 0, s[0:1]
	global_load_dwordx4 v[122:125], v[68:69], off nt
	global_load_dwordx4 v[126:129], v[70:71], off nt
	v_readlane_b32 s0, v244, 46
	v_readlane_b32 s1, v244, 47
	v_pk_fma_f32 v[44:45], v[44:45], v[140:141], v[64:65] op_sel_hi:[1,0,1]
	s_waitcnt vmcnt(19)
	v_pk_fma_f32 v[42:43], v[58:59], v[142:143], v[42:43] op_sel_hi:[1,0,1]
	v_lshl_add_u64 v[68:69], v[66:67], 0, s[0:1]
	v_readlane_b32 s0, v244, 48
	v_readlane_b32 s1, v244, 49
	v_pk_fma_f32 v[44:45], v[60:61], v[142:143], v[44:45] op_sel_hi:[1,0,1]
	s_waitcnt vmcnt(18)
	v_pk_fma_f32 v[34:35], v[34:35], v[144:145], v[42:43] op_sel_hi:[1,0,1]
	v_lshl_add_u64 v[70:71], v[66:67], 0, s[0:1]
	global_load_dwordx4 v[130:133], v[68:69], off nt
	global_load_dwordx4 v[134:137], v[70:71], off nt
	v_readlane_b32 s0, v244, 50
	v_readlane_b32 s1, v244, 51
	v_pk_fma_f32 v[36:37], v[36:37], v[144:145], v[44:45] op_sel_hi:[1,0,1]
	s_waitcnt vmcnt(19)
	v_pk_fma_f32 v[34:35], v[54:55], v[146:147], v[34:35] op_sel_hi:[1,0,1]
	v_lshl_add_u64 v[68:69], v[66:67], 0, s[0:1]
	v_readlane_b32 s0, v244, 52
	v_readlane_b32 s1, v244, 53
	v_pk_fma_f32 v[36:37], v[56:57], v[146:147], v[36:37] op_sel_hi:[1,0,1]
	s_waitcnt vmcnt(18)
	v_pk_fma_f32 v[26:27], v[26:27], v[148:149], v[34:35] op_sel_hi:[1,0,1]
	v_lshl_add_u64 v[70:71], v[66:67], 0, s[0:1]
	v_readlane_b32 s0, v244, 54
	v_readlane_b32 s1, v244, 55
	global_load_dwordx4 v[94:97], v[68:69], off nt
	global_load_dwordx4 v[90:93], v[70:71], off nt
	v_lshl_add_u64 v[68:69], v[66:67], 0, s[0:1]
	v_readlane_b32 s0, v244, 56
	v_readlane_b32 s1, v244, 57
	v_pk_fma_f32 v[28:29], v[28:29], v[148:149], v[36:37] op_sel_hi:[1,0,1]
	s_waitcnt vmcnt(19)
	v_pk_fma_f32 v[26:27], v[50:51], v[150:151], v[26:27] op_sel_hi:[1,0,1]
	v_lshl_add_u64 v[70:71], v[66:67], 0, s[0:1]
	v_readlane_b32 s0, v244, 58
	v_readlane_b32 s1, v244, 59
	global_load_dwordx4 v[86:89], v[68:69], off nt
	global_load_dwordx4 v[82:85], v[70:71], off nt
	v_lshl_add_u64 v[68:69], v[66:67], 0, s[0:1]
	v_readlane_b32 s0, v244, 60
	v_readlane_b32 s1, v244, 61
	v_pk_fma_f32 v[28:29], v[52:53], v[150:151], v[28:29] op_sel_hi:[1,0,1]
	s_waitcnt vmcnt(20)
	v_pk_fma_f32 v[22:23], v[22:23], v[152:153], v[26:27] op_sel_hi:[1,0,1]
	v_lshl_add_u64 v[70:71], v[66:67], 0, s[0:1]
	global_load_dwordx4 v[78:81], v[68:69], off nt
	global_load_dwordx4 v[74:77], v[70:71], off nt
	v_readlane_b32 s0, v244, 62
	v_readlane_b32 s1, v244, 63
	v_pk_fma_f32 v[24:25], v[24:25], v[152:153], v[28:29] op_sel_hi:[1,0,1]
	s_waitcnt vmcnt(21)
	v_pk_fma_f32 v[22:23], v[46:47], v[154:155], v[22:23] op_sel_hi:[1,0,1]
	v_lshl_add_u64 v[68:69], v[66:67], 0, s[0:1]
	v_readlane_b32 s0, v243, 4
	v_readlane_b32 s1, v243, 5
	v_pk_fma_f32 v[24:25], v[48:49], v[154:155], v[24:25] op_sel_hi:[1,0,1]
	s_waitcnt vmcnt(20)
	v_pk_fma_f32 v[18:19], v[18:19], v[156:157], v[22:23] op_sel_hi:[1,0,1]
	v_lshl_add_u64 v[66:67], v[66:67], 0, s[0:1]
	global_load_dwordx4 v[70:73], v[68:69], off nt
	s_nop 0
	global_load_dwordx4 v[66:69], v[66:67], off nt
	v_pk_fma_f32 v[20:21], v[20:21], v[156:157], v[24:25] op_sel_hi:[1,0,1]
	s_waitcnt vmcnt(21)
	v_pk_fma_f32 v[18:19], v[38:39], v[158:159], v[18:19] op_sel_hi:[1,0,1]
	v_pk_fma_f32 v[20:21], v[40:41], v[158:159], v[20:21] op_sel_hi:[1,0,1]
	s_waitcnt vmcnt(20)
	v_pk_fma_f32 v[14:15], v[14:15], v[160:161], v[18:19] op_sel_hi:[1,0,1]
	v_pk_fma_f32 v[16:17], v[16:17], v[160:161], v[20:21] op_sel_hi:[1,0,1]
	s_waitcnt vmcnt(19)
	v_pk_fma_f32 v[18:19], v[30:31], v[162:163], v[14:15] op_sel_hi:[1,0,1]
	v_pk_fma_f32 v[20:21], v[32:33], v[162:163], v[16:17] op_sel_hi:[1,0,1]
	ds_read_b128 v[14:17], v105 offset:64
	s_waitcnt vmcnt(18)
	v_pk_fma_f32 v[10:11], v[10:11], v[164:165], v[18:19] op_sel_hi:[1,0,1]
	v_pk_fma_f32 v[20:21], v[12:13], v[164:165], v[20:21] op_sel_hi:[1,0,1]
	s_waitcnt vmcnt(17)
	v_pk_fma_f32 v[6:7], v[6:7], v[166:167], v[10:11] op_sel_hi:[1,0,1]
	ds_read_b128 v[10:13], v105 offset:80
	s_waitcnt lgkmcnt(1)
	v_sub_f32_e32 v14, v14, v104
	v_mul_f32_e32 v14, 0x3fb8aa3b, v14
	v_exp_f32_e32 v14, v14
	v_pk_fma_f32 v[8:9], v[8:9], v[166:167], v[20:21] op_sel_hi:[1,0,1]
	s_waitcnt vmcnt(16)
	v_pk_fma_f32 v[2:3], v[2:3], v[168:169], v[6:7] op_sel_hi:[1,0,1]
	v_pk_fma_f32 v[4:5], v[4:5], v[168:169], v[8:9] op_sel_hi:[1,0,1]
	v_mul_f32_e32 v6, v139, v14
	s_waitcnt vmcnt(15)
	v_pk_fma_f32 v[2:3], v[106:107], v[6:7], v[2:3] op_sel_hi:[1,0,1]
	v_pk_fma_f32 v[4:5], v[108:109], v[6:7], v[4:5] op_sel_hi:[1,0,1]
	v_sub_f32_e32 v6, v15, v104
	v_mul_f32_e32 v6, 0x3fb8aa3b, v6
	v_sub_f32_e32 v7, v16, v104
	v_exp_f32_e32 v6, v6
	v_mul_f32_e32 v7, 0x3fb8aa3b, v7
	v_exp_f32_e32 v7, v7
	v_mul_f32_e32 v6, v139, v6
	s_waitcnt vmcnt(14)
	v_pk_fma_f32 v[4:5], v[112:113], v[6:7], v[4:5] op_sel_hi:[1,0,1]
	v_pk_fma_f32 v[2:3], v[110:111], v[6:7], v[2:3] op_sel_hi:[1,0,1]
	v_mul_f32_e32 v6, v139, v7
	s_waitcnt vmcnt(13)
	v_pk_fma_f32 v[2:3], v[114:115], v[6:7], v[2:3] op_sel_hi:[1,0,1]
	v_pk_fma_f32 v[4:5], v[116:117], v[6:7], v[4:5] op_sel_hi:[1,0,1]
	v_sub_f32_e32 v6, v17, v104
	v_mul_f32_e32 v6, 0x3fb8aa3b, v6
	s_waitcnt lgkmcnt(0)
	v_sub_f32_e32 v7, v10, v104
	v_exp_f32_e32 v6, v6
	v_mul_f32_e32 v7, 0x3fb8aa3b, v7
	v_exp_f32_e32 v7, v7
	v_mul_f32_e32 v6, v139, v6
	s_waitcnt vmcnt(12)
	v_pk_fma_f32 v[4:5], v[120:121], v[6:7], v[4:5] op_sel_hi:[1,0,1]
	v_pk_fma_f32 v[2:3], v[118:119], v[6:7], v[2:3] op_sel_hi:[1,0,1]
	v_mul_f32_e32 v6, v139, v7
	s_waitcnt vmcnt(11)
	v_pk_fma_f32 v[2:3], v[122:123], v[6:7], v[2:3] op_sel_hi:[1,0,1]
	v_pk_fma_f32 v[4:5], v[124:125], v[6:7], v[4:5] op_sel_hi:[1,0,1]
	v_sub_f32_e32 v6, v11, v104
	v_mul_f32_e32 v6, 0x3fb8aa3b, v6
	v_sub_f32_e32 v7, v12, v104
	v_exp_f32_e32 v6, v6
	v_mul_f32_e32 v7, 0x3fb8aa3b, v7
	v_exp_f32_e32 v7, v7
	v_mul_f32_e32 v6, v139, v6
	s_waitcnt vmcnt(10)
	v_pk_fma_f32 v[4:5], v[128:129], v[6:7], v[4:5] op_sel_hi:[1,0,1]
	v_pk_fma_f32 v[2:3], v[126:127], v[6:7], v[2:3] op_sel_hi:[1,0,1]
	v_mul_f32_e32 v6, v139, v7
	v_sub_f32_e32 v7, v13, v104
	v_mul_f32_e32 v7, 0x3fb8aa3b, v7
	v_exp_f32_e32 v10, v7
	s_waitcnt vmcnt(9)
	v_pk_fma_f32 v[8:9], v[130:131], v[6:7], v[2:3] op_sel_hi:[1,0,1]
	v_pk_fma_f32 v[6:7], v[132:133], v[6:7], v[4:5] op_sel_hi:[1,0,1]
	ds_read_b128 v[2:5], v105 offset:96
	v_mul_f32_e32 v10, v139, v10
	s_waitcnt vmcnt(8)
	v_pk_fma_f32 v[12:13], v[136:137], v[10:11], v[6:7] op_sel_hi:[1,0,1]
	v_pk_fma_f32 v[10:11], v[134:135], v[10:11], v[8:9] op_sel_hi:[1,0,1]
	ds_read_b128 v[6:9], v105 offset:112
	s_waitcnt lgkmcnt(1)
	v_sub_f32_e32 v2, v2, v104
	v_mul_f32_e32 v2, 0x3fb8aa3b, v2
	v_sub_f32_e32 v3, v3, v104
	v_exp_f32_e32 v2, v2
	v_mul_f32_e32 v3, 0x3fb8aa3b, v3
	v_sub_f32_e32 v4, v4, v104
	v_exp_f32_e32 v14, v3
	v_mul_f32_e32 v4, 0x3fb8aa3b, v4
	v_sub_f32_e32 v5, v5, v104
	v_exp_f32_e32 v4, v4
	v_mul_f32_e32 v5, 0x3fb8aa3b, v5
	s_waitcnt lgkmcnt(0)
	v_sub_f32_e32 v6, v6, v104
	v_exp_f32_e32 v5, v5
	v_mul_f32_e32 v6, 0x3fb8aa3b, v6
	v_sub_f32_e32 v7, v7, v104
	v_mul_f32_e32 v2, v139, v2
	v_exp_f32_e32 v6, v6
	v_mul_f32_e32 v7, 0x3fb8aa3b, v7
	s_waitcnt vmcnt(7)
	v_pk_fma_f32 v[10:11], v[94:95], v[2:3], v[10:11] op_sel_hi:[1,0,1]
	v_pk_fma_f32 v[2:3], v[96:97], v[2:3], v[12:13] op_sel_hi:[1,0,1]
	v_mul_f32_e32 v12, v139, v14
	v_exp_f32_e32 v7, v7
	s_waitcnt vmcnt(6)
	v_pk_fma_f32 v[2:3], v[92:93], v[12:13], v[2:3] op_sel_hi:[1,0,1]
	v_pk_fma_f32 v[10:11], v[90:91], v[12:13], v[10:11] op_sel_hi:[1,0,1]
	v_mul_f32_e32 v4, v139, v4
	s_waitcnt vmcnt(5)
	v_pk_fma_f32 v[10:11], v[86:87], v[4:5], v[10:11] op_sel_hi:[1,0,1]
	v_pk_fma_f32 v[2:3], v[88:89], v[4:5], v[2:3] op_sel_hi:[1,0,1]
	v_mul_f32_e32 v4, v139, v5
	s_waitcnt vmcnt(4)
	v_pk_fma_f32 v[2:3], v[84:85], v[4:5], v[2:3] op_sel_hi:[1,0,1]
	v_pk_fma_f32 v[4:5], v[82:83], v[4:5], v[10:11] op_sel_hi:[1,0,1]
	v_mul_f32_e32 v6, v139, v6
	s_waitcnt vmcnt(3)
	v_pk_fma_f32 v[4:5], v[78:79], v[6:7], v[4:5] op_sel_hi:[1,0,1]
	v_pk_fma_f32 v[2:3], v[80:81], v[6:7], v[2:3] op_sel_hi:[1,0,1]
	v_mul_f32_e32 v6, v139, v7
	s_waitcnt vmcnt(2)
	v_pk_fma_f32 v[2:3], v[76:77], v[6:7], v[2:3] op_sel_hi:[1,0,1]
	v_pk_fma_f32 v[4:5], v[74:75], v[6:7], v[4:5] op_sel_hi:[1,0,1]
	v_sub_f32_e32 v6, v8, v104
	v_mul_f32_e32 v6, 0x3fb8aa3b, v6
	v_sub_f32_e32 v7, v9, v104
	v_exp_f32_e32 v6, v6
	v_mul_f32_e32 v7, 0x3fb8aa3b, v7
	v_exp_f32_e32 v7, v7
	v_mul_f32_e32 v6, v139, v6
	s_waitcnt vmcnt(1)
	v_pk_fma_f32 v[8:9], v[70:71], v[6:7], v[4:5] op_sel_hi:[1,0,1]
	v_pk_fma_f32 v[2:3], v[72:73], v[6:7], v[2:3] op_sel_hi:[1,0,1]
	v_mul_f32_e32 v6, v139, v7
	s_waitcnt vmcnt(0)
	v_pk_fma_f32 v[4:5], v[68:69], v[6:7], v[2:3] op_sel_hi:[1,0,1]
	v_pk_fma_f32 v[2:3], v[66:67], v[6:7], v[8:9] op_sel_hi:[1,0,1]
	ds_write_b128 v102, v[2:5] offset:4096
	s_waitcnt lgkmcnt(0)
	s_waitcnt lgkmcnt(0)
	s_barrier
	s_and_saveexec_b64 s[10:11], s[12:13]
	s_cbranch_execz .LBB11_2190
	ds_read2st64_b32 v[2:3], v103 offset0:16 offset1:20
	s_lshl_b64 s[0:1], s[88:89], 1
	s_add_u32 s0, s8, s0
	s_addc_u32 s1, s9, s1
	s_lshl_b32 s48, s68, 1
	s_waitcnt lgkmcnt(0)
	v_add_f32_e32 v2, 0, v2
	v_add_f32_e32 v4, v2, v3
	ds_read2st64_b32 v[2:3], v103 offset0:24 offset1:28
	s_add_u32 s0, s0, s48
	s_addc_u32 s1, s1, 0
	s_waitcnt lgkmcnt(0)
	v_add_f32_e32 v2, v4, v2
	v_add_f32_e32 v4, v2, v3
	ds_read2st64_b32 v[2:3], v103 offset0:32 offset1:36
	s_waitcnt lgkmcnt(0)
	v_add_f32_e32 v2, v4, v2
	v_add_f32_e32 v4, v2, v3
	ds_read2st64_b32 v[2:3], v103 offset0:40 offset1:44
	s_waitcnt lgkmcnt(0)
	v_add_f32_e32 v2, v4, v2
	v_add_f32_e32 v2, v2, v3
	v_cvt_pk_bf16_f32 v4, v2, v1
	v_lshl_add_u64 v[2:3], v[98:99], 1, s[0:1]
	global_store_short v[2:3], v4, off sc1
	s_branch .LBB11_2190

.LBB11_2248:
	s_or_b64 exec, exec, s[14:15]
	v_cmp_eq_u32_e32 vcc, 1, v0
	s_waitcnt vmcnt(0)
	v_readfirstlane_b32 s0, v4
	s_cbranch_vccnz .LBB11_2286
	v_cvt_f32_u32_e32 v4, v2
	v_sub_u32_e32 v5, 0, v2
	v_add_u32_e32 v3, s0, v3
	v_rcp_iflag_f32_e32 v4, v4
	s_nop 0
	v_mul_f32_e32 v4, 0x4f7ffffe, v4
	v_cvt_u32_f32_e32 v4, v4
	v_mul_lo_u32 v5, v5, v4
	v_mul_hi_u32 v5, v4, v5
	v_add_u32_e32 v4, v4, v5
	v_mul_hi_u32 v4, v3, v4
	v_mul_lo_u32 v5, v4, v2
	v_sub_u32_e32 v5, v3, v5
	v_add_u32_e32 v6, 1, v4
	v_cmp_ge_u32_e32 vcc, v5, v2
	v_add_u32_e32 v3, 1, v3
	s_nop 0
	v_cndmask_b32_e32 v4, v4, v6, vcc
	v_sub_u32_e32 v6, v5, v2
	v_cndmask_b32_e32 v5, v5, v6, vcc
	v_add_u32_e32 v6, 1, v4
	v_cmp_ge_u32_e32 vcc, v5, v2
	s_nop 1
	v_cndmask_b32_e32 v4, v4, v6, vcc
	v_mul_lo_u32 v4, v2, v4
	v_add_u32_e32 v2, v4, v2
	v_cmp_eq_u32_e32 vcc, v3, v2
	s_and_saveexec_b64 s[10:11], vcc
	s_cbranch_execz .LBB11_2285
	s_mov_b64 s[14:15], exec
	s_nop 0
	s_waitcnt lgkmcnt(0)
	s_waitcnt vmcnt(0)
	v_mbcnt_lo_u32_b32 v2, s14, 0
	v_mbcnt_hi_u32_b32 v2, s15, v2
	v_cmp_eq_u32_e32 vcc, 0, v2
	s_and_saveexec_b64 s[16:17], vcc
	s_cbranch_execz .LBB11_2252
	s_bcnt1_i32_b64 s0, s[14:15]
	v_mov_b32_e32 v3, s0
	v_readlane_b32 s0, v247, 36
	v_readlane_b32 s1, v247, 37
	s_nop 4
	global_atomic_add v3, v1, v3, s[0:1] sc0

.LBB11_2462:
	s_or_b64 exec, exec, s[30:31]
	s_waitcnt lgkmcnt(0)
	s_waitcnt lgkmcnt(0)
	s_barrier
	ds_read_b128 v[108:111], v106
	ds_read_b128 v[112:115], v106 offset:33024
	v_readlane_b32 s0, v245, 5
	s_andn2_b64 vcc, exec, s[2:3]
	s_waitcnt vmcnt(7) lgkmcnt(1)
	v_mfma_f32_16x16x32_bf16 v[108:111], v[108:111], v[62:65], 0
	v_add_u32_e32 v0, s0, v86
	s_waitcnt lgkmcnt(0)
	v_mfma_f32_16x16x32_bf16 v[62:65], v[112:115], v[62:65], 0
	ds_read_b128 v[112:115], v106 offset:64
	s_waitcnt vmcnt(6) lgkmcnt(0)
	v_mfma_f32_16x16x32_bf16 v[108:111], v[112:115], v[58:61], v[108:111]
	ds_read_b128 v[112:115], v106 offset:33088
	s_waitcnt lgkmcnt(0)
	v_mfma_f32_16x16x32_bf16 v[58:61], v[112:115], v[58:61], v[62:65]
	s_nop 2
	ds_read_b128 v[62:65], v106 offset:128
	s_waitcnt vmcnt(5) lgkmcnt(0)
	v_mfma_f32_16x16x32_bf16 v[62:65], v[62:65], v[54:57], v[108:111]
	s_nop 2
	ds_read_b128 v[108:111], v106 offset:33152
	s_waitcnt lgkmcnt(0)
	v_mfma_f32_16x16x32_bf16 v[54:57], v[108:111], v[54:57], v[58:61]
	s_nop 2
	ds_read_b128 v[58:61], v106 offset:192
	s_waitcnt vmcnt(4) lgkmcnt(0)
	v_mfma_f32_16x16x32_bf16 v[58:61], v[58:61], v[50:53], v[62:65]
	s_nop 2
	ds_read_b128 v[62:65], v106 offset:33216
	s_waitcnt lgkmcnt(0)
	v_mfma_f32_16x16x32_bf16 v[50:53], v[62:65], v[50:53], v[54:57]
	s_nop 2
	ds_read_b128 v[54:57], v106 offset:256
	s_waitcnt vmcnt(3) lgkmcnt(0)
	v_mfma_f32_16x16x32_bf16 v[54:57], v[54:57], v[46:49], v[58:61]
	s_nop 2
	ds_read_b128 v[58:61], v106 offset:33280
	s_waitcnt lgkmcnt(0)
	v_mfma_f32_16x16x32_bf16 v[46:49], v[58:61], v[46:49], v[50:53]
	s_nop 2
	ds_read_b128 v[50:53], v106 offset:320
	s_waitcnt vmcnt(2) lgkmcnt(0)
	v_mfma_f32_16x16x32_bf16 v[50:53], v[50:53], v[42:45], v[54:57]
	s_nop 2
	ds_read_b128 v[54:57], v106 offset:33344
	s_waitcnt lgkmcnt(0)
	v_mfma_f32_16x16x32_bf16 v[42:45], v[54:57], v[42:45], v[46:49]
	s_nop 2
	ds_read_b128 v[46:49], v106 offset:384
	s_waitcnt vmcnt(1) lgkmcnt(0)
	v_mfma_f32_16x16x32_bf16 v[46:49], v[46:49], v[38:41], v[50:53]
	s_nop 2
	ds_read_b128 v[50:53], v106 offset:33408
	s_waitcnt lgkmcnt(0)
	v_mfma_f32_16x16x32_bf16 v[42:45], v[50:53], v[38:41], v[42:45]
	ds_read_b128 v[38:41], v106 offset:448
	s_waitcnt vmcnt(0) lgkmcnt(0)
	v_mfma_f32_16x16x32_bf16 v[38:41], v[38:41], v[34:37], v[46:49]
	s_nop 2
	ds_read_b128 v[46:49], v106 offset:33472
	s_waitcnt lgkmcnt(0)
	v_mfma_f32_16x16x32_bf16 v[34:37], v[46:49], v[34:37], v[42:45]
	s_nop 1
	ds_write_b128 v0, v[38:41]
	s_nop 4
	ds_write_b128 v0, v[34:37] offset:1024
	s_waitcnt lgkmcnt(0)
	s_waitcnt lgkmcnt(0)
	s_barrier
	s_cbranch_vccnz .LBB11_2429
	v_readlane_b32 s0, v245, 6
	s_nop 1
	v_add_u32_e32 v0, s0, v86
	ds_read_b128 v[42:45], v0 offset:4096
	s_lshl_b32 s0, s9, 17
	s_waitcnt lgkmcnt(0)
	v_pk_add_f32 v[44:45], v[40:41], v[44:45]
	v_pk_add_f32 v[42:43], v[38:39], v[42:43]
	ds_read_b128 v[38:41], v0 offset:5120
	s_waitcnt lgkmcnt(0)
	v_pk_add_f32 v[40:41], v[36:37], v[40:41]
	v_pk_add_f32 v[38:39], v[34:35], v[38:39]
	ds_read_b128 v[34:37], v0 offset:8192
	s_waitcnt lgkmcnt(0)
	v_pk_add_f32 v[44:45], v[44:45], v[36:37]
	v_pk_add_f32 v[42:43], v[42:43], v[34:35]
	ds_read_b128 v[34:37], v0 offset:9216
	s_waitcnt lgkmcnt(0)
	v_pk_add_f32 v[40:41], v[40:41], v[36:37]
	v_pk_add_f32 v[46:47], v[38:39], v[34:35]
	ds_read_b128 v[34:37], v0 offset:12288
	s_waitcnt lgkmcnt(0)
	v_pk_add_f32 v[44:45], v[44:45], v[36:37]
	ds_read_b128 v[36:39], v0 offset:13312
	v_pk_add_f32 v[42:43], v[42:43], v[34:35]
	v_subrev_u32_e32 v0, s0, v97
	s_waitcnt lgkmcnt(0)
	v_pk_add_f32 v[34:35], v[40:41], v[38:39]
	v_add_u32_e32 v38, s34, v87
	v_lshlrev_b64 v[40:41], 1, v[0:1]
	v_ashrrev_i32_e32 v39, 31, v38
	v_pk_add_f32 v[36:37], v[46:47], v[36:37]
	v_lshl_add_u64 v[46:47], s[66:67], 0, v[40:41]
	v_lshlrev_b64 v[48:49], 1, v[38:39]
	v_lshl_add_u64 v[38:39], v[46:47], 0, v[48:49]
	v_lshl_add_u64 v[40:41], s[64:65], 0, v[40:41]
	v_lshl_add_u64 v[40:41], v[40:41], 0, v[48:49]
	global_load_dwordx2 v[46:47], v[38:39], off
	global_load_dwordx2 v[48:49], v[40:41], off
	s_waitcnt vmcnt(1)
	v_lshlrev_b32_e32 v50, 16, v46
	v_and_b32_e32 v51, 0xffff0000, v46
	s_waitcnt vmcnt(0)
	v_lshlrev_b32_e32 v52, 16, v48
	v_and_b32_e32 v53, 0xffff0000, v48
	v_lshlrev_b32_e32 v46, 16, v47
	v_and_b32_e32 v47, 0xffff0000, v47
	v_lshlrev_b32_e32 v48, 16, v49
	v_and_b32_e32 v49, 0xffff0000, v49
	v_pk_add_f32 v[50:51], v[50:51], v[52:53]
	v_pk_add_f32 v[46:47], v[46:47], v[48:49]
	v_pk_add_f32 v[42:43], v[42:43], v[50:51]
	v_pk_add_f32 v[44:45], v[44:45], v[46:47]
	v_cvt_pk_bf16_f32 v46, v42, v43
	s_nop 0
	v_cvt_pk_bf16_f32 v47, v44, v45
	v_lshlrev_b32_e32 v48, 16, v46
	v_and_b32_e32 v49, 0xffff0000, v46
	v_lshlrev_b32_e32 v50, 16, v47
	v_and_b32_e32 v51, 0xffff0000, v47
	v_sub_f32_e32 v0, v44, v50
	v_sub_f32_e32 v44, v45, v51
	v_sub_f32_e32 v42, v42, v48
	v_sub_f32_e32 v43, v43, v49
	v_cvt_pk_bf16_f32 v42, v42, v43
	v_cvt_pk_bf16_f32 v43, v0, v44
	global_store_dwordx2 v[38:39], v[46:47], off sc1
	global_store_dwordx2 v[40:41], v[42:43], off sc1
	v_lshlrev_b32_e32 v44, 16, v42
	v_and_b32_e32 v45, 0xffff0000, v42
	v_lshlrev_b32_e32 v52, 16, v43
	v_and_b32_e32 v53, 0xffff0000, v43
	v_pk_add_f32 v[50:51], v[50:51], v[52:53]
	v_pk_add_f32 v[44:45], v[48:49], v[44:45]
	v_mul_f32_e32 v42, v51, v51
	v_mul_f32_e32 v0, v45, v45
	v_fmac_f32_e32 v0, v44, v44
	v_fmac_f32_e32 v42, v50, v50
	v_add_f32_e32 v0, v0, v42
	global_load_dwordx2 v[42:43], v[38:39], off offset:32
	global_load_dwordx2 v[44:45], v[40:41], off offset:32
	s_waitcnt vmcnt(1)
	v_lshlrev_b32_e32 v46, 16, v42
	v_and_b32_e32 v47, 0xffff0000, v42
	s_waitcnt vmcnt(0)
	v_lshlrev_b32_e32 v48, 16, v44
	v_and_b32_e32 v49, 0xffff0000, v44
	v_lshlrev_b32_e32 v42, 16, v43
	v_and_b32_e32 v43, 0xffff0000, v43
	v_lshlrev_b32_e32 v44, 16, v45
	v_and_b32_e32 v45, 0xffff0000, v45
	v_pk_add_f32 v[46:47], v[46:47], v[48:49]
	v_pk_add_f32 v[42:43], v[42:43], v[44:45]
	v_pk_add_f32 v[36:37], v[36:37], v[46:47]
	v_pk_add_f32 v[34:35], v[34:35], v[42:43]
	v_cvt_pk_bf16_f32 v42, v36, v37
	s_nop 0
	v_cvt_pk_bf16_f32 v43, v34, v35
	v_lshlrev_b32_e32 v44, 16, v42
	v_and_b32_e32 v45, 0xffff0000, v42
	v_lshlrev_b32_e32 v46, 16, v43
	v_and_b32_e32 v47, 0xffff0000, v43
	v_sub_f32_e32 v48, v34, v46
	v_sub_f32_e32 v35, v35, v47
	v_sub_f32_e32 v34, v36, v44
	v_sub_f32_e32 v36, v37, v45
	v_cvt_pk_bf16_f32 v34, v34, v36
	v_cvt_pk_bf16_f32 v35, v48, v35
	global_store_dwordx2 v[38:39], v[42:43], off offset:32 sc1
	global_store_dwordx2 v[40:41], v[34:35], off offset:32 sc1
	v_lshlrev_b32_e32 v36, 16, v34
	v_and_b32_e32 v37, 0xffff0000, v34
	v_lshlrev_b32_e32 v48, 16, v35
	v_and_b32_e32 v49, 0xffff0000, v35
	v_pk_add_f32 v[46:47], v[46:47], v[48:49]
	v_pk_add_f32 v[36:37], v[44:45], v[36:37]
	v_mul_f32_e32 v35, v47, v47
	v_mul_f32_e32 v34, v37, v37
	v_fmac_f32_e32 v34, v36, v36
	v_fmac_f32_e32 v35, v46, v46
	v_add_f32_e32 v34, v34, v35
	v_add_f32_e32 v0, v0, v34
	ds_bpermute_b32 v34, v204, v0
	s_waitcnt lgkmcnt(0)
	v_add_f32_e32 v34, v0, v34
	ds_bpermute_b32 v35, v205, v34
	s_and_saveexec_b64 s[30:31], s[10:11]
	s_cbranch_execz .LBB11_2428
	v_add_u32_e32 v0, 0x4000, v84
	v_lshl_add_u64 v[36:37], v[0:1], 2, s[28:29]
	s_waitcnt lgkmcnt(0)
	v_add_f32_e32 v0, v34, v35
	global_atomic_add_f32 v[36:37], v0, off
	s_branch .LBB11_2428

.LBB11_2668:
	s_and_b32 s0, s6, 0xffffff00
	s_and_b32 s1, s10, 0x70
	s_or_b32 s0, s0, s1
	v_add_u32_e32 v168, s0, v52
	v_add_u32_e32 v170, s0, v53
	v_add_u32_e32 v172, s0, v54
	v_add_u32_e32 v174, s0, v55
	v_add_u32_e32 v176, s0, v56
	v_add_u32_e32 v178, s0, v57
	v_add_u32_e32 v180, s0, v58
	v_add_u32_e32 v182, s0, v59
	v_ashrrev_i32_e32 v169, 31, v168
	v_ashrrev_i32_e32 v171, 31, v170
	v_ashrrev_i32_e32 v173, 31, v172
	v_ashrrev_i32_e32 v175, 31, v174
	v_ashrrev_i32_e32 v177, 31, v176
	v_ashrrev_i32_e32 v179, 31, v178
	v_ashrrev_i32_e32 v181, 31, v180
	v_ashrrev_i32_e32 v183, 31, v182
	v_lshlrev_b64 v[168:169], 11, v[168:169]
	v_lshlrev_b64 v[170:171], 11, v[170:171]
	v_lshlrev_b64 v[172:173], 11, v[172:173]
	v_lshlrev_b64 v[174:175], 11, v[174:175]
	v_lshlrev_b64 v[176:177], 11, v[176:177]
	v_lshlrev_b64 v[178:179], 11, v[178:179]
	v_lshlrev_b64 v[180:181], 11, v[180:181]
	v_lshlrev_b64 v[182:183], 11, v[182:183]
	v_lshl_add_u64 v[168:169], v[36:37], 0, v[168:169]
	v_lshl_add_u64 v[190:191], v[38:39], 0, v[170:171]
	v_lshl_add_u64 v[192:193], v[40:41], 0, v[172:173]
	v_lshl_add_u64 v[194:195], v[42:43], 0, v[174:175]
	v_lshl_add_u64 v[196:197], v[44:45], 0, v[176:177]
	v_lshl_add_u64 v[214:215], v[46:47], 0, v[178:179]
	v_lshl_add_u64 v[216:217], v[48:49], 0, v[180:181]
	v_lshl_add_u64 v[218:219], v[50:51], 0, v[182:183]
	global_load_dwordx4 v[14:17], v[30:31], off
	global_load_dwordx4 v[18:21], v[30:31], off offset:64
	global_load_dwordx4 v[22:25], v[30:31], off offset:128
	global_load_dwordx4 v[26:29], v[30:31], off offset:192
	global_load_dwordx4 v[68:71], v[30:31], off offset:256
	global_load_dwordx4 v[72:75], v[30:31], off offset:320
	global_load_dwordx4 v[76:79], v[30:31], off offset:384
	global_load_dwordx4 v[80:83], v[30:31], off offset:448
	global_load_dwordx4 v[84:87], v[30:31], off offset:512
	global_load_dwordx4 v[88:91], v[30:31], off offset:576
	global_load_dwordx4 v[92:95], v[30:31], off offset:640
	global_load_dwordx4 v[96:99], v[30:31], off offset:704
	global_load_dwordx4 v[100:103], v[30:31], off offset:768
	global_load_dwordx4 v[104:107], v[30:31], off offset:832
	global_load_dwordx4 v[108:111], v[30:31], off offset:896
	global_load_dwordx4 v[112:115], v[30:31], off offset:960
	global_load_dwordx4 v[116:119], v[30:31], off offset:1024
	global_load_dwordx4 v[120:123], v[30:31], off offset:1088
	global_load_dwordx4 v[124:127], v[30:31], off offset:1152
	global_load_dwordx4 v[128:131], v[30:31], off offset:1216
	global_load_dwordx4 v[132:135], v[30:31], off offset:1280
	global_load_dwordx4 v[136:139], v[30:31], off offset:1344
	global_load_dwordx4 v[140:143], v[30:31], off offset:1408
	global_load_dwordx4 v[144:147], v[30:31], off offset:1472
	global_load_dwordx4 v[148:151], v[30:31], off offset:1536
	global_load_dwordx4 v[152:155], v[30:31], off offset:1600
	global_load_dwordx4 v[156:159], v[30:31], off offset:1664
	global_load_dwordx4 v[160:163], v[30:31], off offset:1728
	global_load_dwordx4 v[164:167], v[30:31], off offset:1792
	global_load_dwordx4 v[10:13], v[30:31], off offset:1856
	global_load_dwordx4 v[6:9], v[30:31], off offset:1920
	global_load_dwordx4 v[2:5], v[30:31], off offset:1984
	s_barrier
	global_load_dwordx4 v[168:171], v[168:169], off
	s_nop 0
	global_load_dwordx4 v[172:175], v[190:191], off
	global_load_dwordx4 v[176:179], v[192:193], off
	global_load_dwordx4 v[180:183], v[194:195], off
	s_nop 0
	global_load_dwordx4 v[190:193], v[196:197], off
	s_nop 0
	global_load_dwordx4 v[194:197], v[214:215], off
	s_nop 0
	global_load_dwordx4 v[214:217], v[216:217], off
	s_nop 0
	global_load_dwordx4 v[218:221], v[218:219], off
	s_ashr_i32 s11, s10, 31
	s_addk_i32 s7, 0x80
	s_addk_i32 s6, 0x1000
	s_waitcnt vmcnt(7)
	ds_write_b128 v60, v[168:171]
	s_waitcnt vmcnt(6)
	ds_write_b128 v61, v[172:175]
	s_waitcnt vmcnt(5)
	ds_write_b128 v62, v[176:179]
	s_waitcnt vmcnt(4)
	ds_write_b128 v63, v[180:183]
	s_waitcnt vmcnt(3)
	ds_write_b128 v64, v[190:193]
	s_waitcnt vmcnt(2)
	ds_write_b128 v65, v[194:197]
	s_waitcnt vmcnt(1)
	ds_write_b128 v66, v[214:217]
	s_waitcnt vmcnt(0)
	ds_write_b128 v67, v[218:221]
	s_waitcnt lgkmcnt(0)
	s_waitcnt lgkmcnt(0)
	s_barrier
	ds_read_b128 v[168:171], v0
	ds_read_b128 v[172:175], v0 offset:64
	ds_read_b128 v[176:179], v0 offset:33024
	ds_read_b128 v[180:183], v0 offset:33088
	s_waitcnt lgkmcnt(3)
	v_mfma_f32_16x16x32_bf16 v[168:171], v[168:171], v[14:17], 0
	s_waitcnt lgkmcnt(1)
	v_mfma_f32_16x16x32_bf16 v[14:17], v[176:179], v[14:17], 0
	v_mfma_f32_16x16x32_bf16 v[168:171], v[172:175], v[18:21], v[168:171]
	s_waitcnt lgkmcnt(0)
	v_mfma_f32_16x16x32_bf16 v[14:17], v[180:183], v[18:21], v[14:17]
	ds_read_b128 v[18:21], v0 offset:128
	ds_read_b128 v[172:175], v0 offset:192
	s_waitcnt lgkmcnt(1)
	v_mfma_f32_16x16x32_bf16 v[18:21], v[18:21], v[22:25], v[168:171]
	s_nop 2
	ds_read_b128 v[168:171], v0 offset:33152
	ds_read_b128 v[176:179], v0 offset:33216
	s_waitcnt lgkmcnt(1)
	v_mfma_f32_16x16x32_bf16 v[14:17], v[168:171], v[22:25], v[14:17]
	v_mfma_f32_16x16x32_bf16 v[18:21], v[172:175], v[26:29], v[18:21]
	s_waitcnt lgkmcnt(0)
	v_mfma_f32_16x16x32_bf16 v[14:17], v[176:179], v[26:29], v[14:17]
	ds_read_b128 v[22:25], v0 offset:256
	ds_read_b128 v[26:29], v0 offset:320
	s_waitcnt lgkmcnt(1)
	v_mfma_f32_16x16x32_bf16 v[18:21], v[22:25], v[68:71], v[18:21]
	ds_read_b128 v[22:25], v0 offset:33280
	ds_read_b128 v[168:171], v0 offset:33344
	s_waitcnt lgkmcnt(1)
	v_mfma_f32_16x16x32_bf16 v[14:17], v[22:25], v[68:71], v[14:17]
	v_mfma_f32_16x16x32_bf16 v[18:21], v[26:29], v[72:75], v[18:21]
	ds_read_b128 v[22:25], v0 offset:384
	ds_read_b128 v[26:29], v0 offset:448
	s_waitcnt lgkmcnt(2)
	v_mfma_f32_16x16x32_bf16 v[14:17], v[168:171], v[72:75], v[14:17]
	s_waitcnt lgkmcnt(1)
	v_mfma_f32_16x16x32_bf16 v[18:21], v[22:25], v[76:79], v[18:21]
	ds_read_b128 v[22:25], v0 offset:33408
	ds_read_b128 v[68:71], v0 offset:33472
	s_waitcnt lgkmcnt(1)
	v_mfma_f32_16x16x32_bf16 v[14:17], v[22:25], v[76:79], v[14:17]
	v_mfma_f32_16x16x32_bf16 v[18:21], v[26:29], v[80:83], v[18:21]
	ds_read_b128 v[22:25], v0 offset:512
	ds_read_b128 v[26:29], v0 offset:576
	s_waitcnt lgkmcnt(2)
	v_mfma_f32_16x16x32_bf16 v[14:17], v[68:71], v[80:83], v[14:17]
	s_waitcnt lgkmcnt(1)
	v_mfma_f32_16x16x32_bf16 v[18:21], v[22:25], v[84:87], v[18:21]
	ds_read_b128 v[22:25], v0 offset:33536
	ds_read_b128 v[68:71], v0 offset:33600
	s_waitcnt lgkmcnt(1)
	v_mfma_f32_16x16x32_bf16 v[14:17], v[22:25], v[84:87], v[14:17]
	v_mfma_f32_16x16x32_bf16 v[18:21], v[26:29], v[88:91], v[18:21]
	ds_read_b128 v[22:25], v0 offset:640
	ds_read_b128 v[26:29], v0 offset:704
	s_waitcnt lgkmcnt(2)
	v_mfma_f32_16x16x32_bf16 v[14:17], v[68:71], v[88:91], v[14:17]
	s_waitcnt lgkmcnt(1)
	v_mfma_f32_16x16x32_bf16 v[18:21], v[22:25], v[92:95], v[18:21]
	ds_read_b128 v[22:25], v0 offset:33664
	ds_read_b128 v[68:71], v0 offset:33728
	s_waitcnt lgkmcnt(1)
	v_mfma_f32_16x16x32_bf16 v[14:17], v[22:25], v[92:95], v[14:17]
	v_mfma_f32_16x16x32_bf16 v[18:21], v[26:29], v[96:99], v[18:21]
	ds_read_b128 v[22:25], v0 offset:768
	ds_read_b128 v[26:29], v0 offset:832
	s_waitcnt lgkmcnt(2)
	v_mfma_f32_16x16x32_bf16 v[14:17], v[68:71], v[96:99], v[14:17]
	s_waitcnt lgkmcnt(1)
	v_mfma_f32_16x16x32_bf16 v[18:21], v[22:25], v[100:103], v[18:21]
	ds_read_b128 v[22:25], v0 offset:33792
	ds_read_b128 v[68:71], v0 offset:33856
	s_waitcnt lgkmcnt(1)
	v_mfma_f32_16x16x32_bf16 v[14:17], v[22:25], v[100:103], v[14:17]
	v_mfma_f32_16x16x32_bf16 v[18:21], v[26:29], v[104:107], v[18:21]
	ds_read_b128 v[22:25], v0 offset:896
	ds_read_b128 v[26:29], v0 offset:960
	s_waitcnt lgkmcnt(2)
	v_mfma_f32_16x16x32_bf16 v[14:17], v[68:71], v[104:107], v[14:17]
	s_waitcnt lgkmcnt(1)
	v_mfma_f32_16x16x32_bf16 v[18:21], v[22:25], v[108:111], v[18:21]
	ds_read_b128 v[22:25], v0 offset:33920
	ds_read_b128 v[68:71], v0 offset:33984
	s_waitcnt lgkmcnt(1)
	v_mfma_f32_16x16x32_bf16 v[14:17], v[22:25], v[108:111], v[14:17]
	v_mfma_f32_16x16x32_bf16 v[18:21], v[26:29], v[112:115], v[18:21]
	ds_read_b128 v[22:25], v0 offset:1024
	ds_read_b128 v[26:29], v0 offset:1088
	s_waitcnt lgkmcnt(2)
	v_mfma_f32_16x16x32_bf16 v[14:17], v[68:71], v[112:115], v[14:17]
	s_waitcnt lgkmcnt(1)
	v_mfma_f32_16x16x32_bf16 v[18:21], v[22:25], v[116:119], v[18:21]
	ds_read_b128 v[22:25], v0 offset:34048
	ds_read_b128 v[68:71], v0 offset:34112
	s_waitcnt lgkmcnt(1)
	v_mfma_f32_16x16x32_bf16 v[14:17], v[22:25], v[116:119], v[14:17]
	v_mfma_f32_16x16x32_bf16 v[18:21], v[26:29], v[120:123], v[18:21]
	ds_read_b128 v[22:25], v0 offset:1152
	ds_read_b128 v[26:29], v0 offset:1216
	s_waitcnt lgkmcnt(2)
	v_mfma_f32_16x16x32_bf16 v[14:17], v[68:71], v[120:123], v[14:17]
	s_waitcnt lgkmcnt(1)
	v_mfma_f32_16x16x32_bf16 v[18:21], v[22:25], v[124:127], v[18:21]
	ds_read_b128 v[22:25], v0 offset:34176
	ds_read_b128 v[68:71], v0 offset:34240
	s_waitcnt lgkmcnt(1)
	v_mfma_f32_16x16x32_bf16 v[14:17], v[22:25], v[124:127], v[14:17]
	v_mfma_f32_16x16x32_bf16 v[18:21], v[26:29], v[128:131], v[18:21]
	ds_read_b128 v[22:25], v0 offset:1280
	ds_read_b128 v[26:29], v0 offset:1344
	s_waitcnt lgkmcnt(2)
	v_mfma_f32_16x16x32_bf16 v[14:17], v[68:71], v[128:131], v[14:17]
	s_waitcnt lgkmcnt(1)
	v_mfma_f32_16x16x32_bf16 v[18:21], v[22:25], v[132:135], v[18:21]
	ds_read_b128 v[22:25], v0 offset:34304
	ds_read_b128 v[68:71], v0 offset:34368
	s_waitcnt lgkmcnt(1)
	v_mfma_f32_16x16x32_bf16 v[14:17], v[22:25], v[132:135], v[14:17]
	v_mfma_f32_16x16x32_bf16 v[18:21], v[26:29], v[136:139], v[18:21]
	ds_read_b128 v[22:25], v0 offset:1408
	ds_read_b128 v[26:29], v0 offset:1472
	s_waitcnt lgkmcnt(2)
	v_mfma_f32_16x16x32_bf16 v[14:17], v[68:71], v[136:139], v[14:17]
	s_waitcnt lgkmcnt(1)
	v_mfma_f32_16x16x32_bf16 v[18:21], v[22:25], v[140:143], v[18:21]
	ds_read_b128 v[22:25], v0 offset:34432
	ds_read_b128 v[68:71], v0 offset:34496
	s_waitcnt lgkmcnt(1)
	v_mfma_f32_16x16x32_bf16 v[14:17], v[22:25], v[140:143], v[14:17]
	v_mfma_f32_16x16x32_bf16 v[18:21], v[26:29], v[144:147], v[18:21]
	ds_read_b128 v[22:25], v0 offset:1536
	ds_read_b128 v[26:29], v0 offset:1600
	s_waitcnt lgkmcnt(2)
	v_mfma_f32_16x16x32_bf16 v[14:17], v[68:71], v[144:147], v[14:17]
	s_waitcnt lgkmcnt(1)
	v_mfma_f32_16x16x32_bf16 v[18:21], v[22:25], v[148:151], v[18:21]
	ds_read_b128 v[22:25], v0 offset:34560
	ds_read_b128 v[68:71], v0 offset:34624
	s_waitcnt lgkmcnt(1)
	v_mfma_f32_16x16x32_bf16 v[14:17], v[22:25], v[148:151], v[14:17]
	v_mfma_f32_16x16x32_bf16 v[18:21], v[26:29], v[152:155], v[18:21]
	ds_read_b128 v[22:25], v0 offset:1664
	ds_read_b128 v[26:29], v0 offset:1728
	s_waitcnt lgkmcnt(2)
	v_mfma_f32_16x16x32_bf16 v[14:17], v[68:71], v[152:155], v[14:17]
	s_waitcnt lgkmcnt(1)
	v_mfma_f32_16x16x32_bf16 v[18:21], v[22:25], v[156:159], v[18:21]
	ds_read_b128 v[22:25], v0 offset:34688
	ds_read_b128 v[70:73], v0 offset:34752
	global_load_dword v68, v[32:33], off
	s_waitcnt vmcnt(0)
	v_fmamk_f32 v68, v68, 0x3a800000, v206
	s_waitcnt lgkmcnt(1)
	v_mfma_f32_16x16x32_bf16 v[14:17], v[22:25], v[156:159], v[14:17]
	v_cmp_gt_f32_e32 vcc, s77, v68
	v_mfma_f32_16x16x32_bf16 v[18:21], v[26:29], v[160:163], v[18:21]
	s_waitcnt lgkmcnt(0)
	v_mfma_f32_16x16x32_bf16 v[70:73], v[70:73], v[160:163], v[14:17]
	s_nop 3
	ds_read_b128 v[14:17], v0 offset:1792
	ds_read_b128 v[22:25], v0 offset:1856
	s_waitcnt lgkmcnt(1)
	v_mfma_f32_16x16x32_bf16 v[26:29], v[14:17], v[164:167], v[18:21]
	s_nop 2
	ds_read_b128 v[18:21], v0 offset:34816
	ds_read_b128 v[14:17], v0 offset:34880
	s_waitcnt lgkmcnt(1)
	v_mfma_f32_16x16x32_bf16 v[18:21], v[18:21], v[164:167], v[70:73]
	s_nop 2
	v_lshl_add_u64 v[70:71], s[10:11], 1, v[34:35]
	v_mfma_f32_16x16x32_bf16 v[22:25], v[22:25], v[10:13], v[26:29]
	s_addk_i32 s10, 0x800
	s_cmp_lt_i32 s7, 48
	s_waitcnt lgkmcnt(0)
	v_mfma_f32_16x16x32_bf16 v[10:13], v[14:17], v[10:13], v[18:21]
	ds_read_b128 v[14:17], v0 offset:1920
	s_nop 1
	ds_read_b128 v[18:21], v0 offset:1984
	s_waitcnt lgkmcnt(1)
	v_mfma_f32_16x16x32_bf16 v[14:17], v[14:17], v[6:9], v[22:25]
	s_nop 2
	ds_read_b128 v[22:25], v0 offset:34944
	ds_read_b128 v[26:29], v0 offset:35008
	s_waitcnt lgkmcnt(1)
	v_mfma_f32_16x16x32_bf16 v[6:9], v[22:25], v[6:9], v[10:13]
	s_nop 2
	v_mul_f32_e32 v10, 0x4b800000, v68
	v_cndmask_b32_e32 v22, v68, v10, vcc
	v_mfma_f32_16x16x32_bf16 v[10:13], v[18:21], v[2:5], v[14:17]
	s_nop 2
	v_rsq_f32_e32 v14, v22
	s_waitcnt lgkmcnt(0)
	v_mfma_f32_16x16x32_bf16 v[2:5], v[26:29], v[2:5], v[6:9]
	v_mul_f32_e32 v15, 0x45800000, v14
	v_cndmask_b32_e32 v14, v14, v15, vcc
	s_nop 0
	v_mov_b32_e32 v7, v10
	s_nop 3
	v_mov_b32_e32 v6, v2
	v_mov_b32_e32 v10, v3
	v_mov_b32_e32 v2, v4
	v_mov_b32_e32 v3, v12
	v_mov_b32_e32 v12, v5
	v_pk_mul_f32 v[2:3], v[2:3], v[14:15] op_sel_hi:[1,0]
	v_pk_mul_f32 v[4:5], v[6:7], v[14:15] op_sel_hi:[1,0]
	v_pk_mul_f32 v[6:7], v[10:11], v[14:15] op_sel_hi:[1,0]
	v_pk_mul_f32 v[8:9], v[12:13], v[14:15] op_sel_hi:[1,0]
	v_mul_f32_e32 v12, 0xbfb8aa3b, v3
	v_mul_f32_e32 v10, 0xbfb8aa3b, v5
	v_mul_f32_e32 v11, 0xbfb8aa3b, v7
	v_mul_f32_e32 v13, 0xbfb8aa3b, v9
	v_exp_f32_e32 v12, v12
	v_exp_f32_e32 v10, v10
	v_exp_f32_e32 v11, v11
	v_exp_f32_e32 v13, v13
	v_add_f32_e32 v12, 1.0, v12
	v_add_f32_e32 v10, 1.0, v10
	v_add_f32_e32 v11, 1.0, v11
	v_add_f32_e32 v13, 1.0, v13
	v_rcp_f32_e32 v12, v12
	v_rcp_f32_e32 v10, v10
	v_rcp_f32_e32 v11, v11
	v_rcp_f32_e32 v13, v13
	v_mul_f32_e32 v3, v3, v12
	v_mul_f32_e32 v5, v5, v10
	v_mul_f32_e32 v7, v7, v11
	v_mul_f32_e32 v9, v9, v13
	v_mul_f32_e32 v3, v2, v3
	v_mul_f32_e32 v4, v4, v5
	v_mul_f32_e32 v5, v6, v7
	v_mul_f32_e32 v6, v8, v9
	v_cvt_pk_bf16_f32 v2, v4, v5
	v_cvt_pk_bf16_f32 v3, v3, v6
	global_store_dwordx2 v[70:71], v[2:3], off sc1
	s_cbranch_scc1 .LBB11_2668

.LBB11_2915:
	s_or_b64 exec, exec, s[38:39]
	s_waitcnt lgkmcnt(0)
	s_waitcnt lgkmcnt(0)
	s_barrier
	ds_read_b128 v[192:195], v191
	v_readlane_b32 s0, v243, 0
	s_andn2_b64 vcc, exec, s[2:3]
	s_waitcnt vmcnt(21) lgkmcnt(0)
	v_mfma_f32_16x16x32_bf16 v[130:133], v[192:195], v[130:133], 0
	ds_read_b128 v[192:195], v191 offset:64
	v_add_u32_e32 v0, s0, v158
	s_waitcnt vmcnt(20) lgkmcnt(0)
	v_mfma_f32_16x16x32_bf16 v[126:129], v[192:195], v[126:129], v[130:133]
	s_nop 3
	ds_read_b128 v[130:133], v191 offset:128
	s_waitcnt vmcnt(19) lgkmcnt(0)
	v_mfma_f32_16x16x32_bf16 v[122:125], v[130:133], v[122:125], v[126:129]
	s_nop 2
	ds_read_b128 v[126:129], v191 offset:192
	s_waitcnt vmcnt(18) lgkmcnt(0)
	v_mfma_f32_16x16x32_bf16 v[118:121], v[126:129], v[118:121], v[122:125]
	s_nop 2
	ds_read_b128 v[122:125], v191 offset:256
	s_waitcnt vmcnt(17) lgkmcnt(0)
	v_mfma_f32_16x16x32_bf16 v[114:117], v[122:125], v[114:117], v[118:121]
	s_nop 2
	ds_read_b128 v[118:121], v191 offset:320
	s_waitcnt vmcnt(16) lgkmcnt(0)
	v_mfma_f32_16x16x32_bf16 v[110:113], v[118:121], v[110:113], v[114:117]
	s_nop 2
	ds_read_b128 v[114:117], v191 offset:384
	s_waitcnt vmcnt(15) lgkmcnt(0)
	v_mfma_f32_16x16x32_bf16 v[106:109], v[114:117], v[106:109], v[110:113]
	s_nop 2
	ds_read_b128 v[110:113], v191 offset:448
	s_waitcnt vmcnt(14) lgkmcnt(0)
	v_mfma_f32_16x16x32_bf16 v[102:105], v[110:113], v[102:105], v[106:109]
	s_nop 2
	ds_read_b128 v[106:109], v191 offset:512
	s_waitcnt vmcnt(13) lgkmcnt(0)
	v_mfma_f32_16x16x32_bf16 v[98:101], v[106:109], v[98:101], v[102:105]
	s_nop 2
	ds_read_b128 v[102:105], v191 offset:576
	s_waitcnt vmcnt(12) lgkmcnt(0)
	v_mfma_f32_16x16x32_bf16 v[94:97], v[102:105], v[94:97], v[98:101]
	s_nop 2
	ds_read_b128 v[98:101], v191 offset:640
	s_waitcnt vmcnt(11) lgkmcnt(0)
	v_mfma_f32_16x16x32_bf16 v[90:93], v[98:101], v[90:93], v[94:97]
	s_nop 2
	ds_read_b128 v[94:97], v191 offset:704
	s_waitcnt vmcnt(10) lgkmcnt(0)
	v_mfma_f32_16x16x32_bf16 v[86:89], v[94:97], v[86:89], v[90:93]
	s_nop 2
	ds_read_b128 v[90:93], v191 offset:768
	s_waitcnt vmcnt(9) lgkmcnt(0)
	v_mfma_f32_16x16x32_bf16 v[82:85], v[90:93], v[82:85], v[86:89]
	s_nop 2
	ds_read_b128 v[86:89], v191 offset:832
	s_waitcnt vmcnt(8) lgkmcnt(0)
	v_mfma_f32_16x16x32_bf16 v[78:81], v[86:89], v[78:81], v[82:85]
	s_nop 2
	ds_read_b128 v[82:85], v191 offset:896
	s_waitcnt vmcnt(7) lgkmcnt(0)
	v_mfma_f32_16x16x32_bf16 v[74:77], v[82:85], v[74:77], v[78:81]
	s_nop 2
	ds_read_b128 v[78:81], v191 offset:960
	s_waitcnt vmcnt(6) lgkmcnt(0)
	v_mfma_f32_16x16x32_bf16 v[70:73], v[78:81], v[70:73], v[74:77]
	s_nop 2
	ds_read_b128 v[74:77], v191 offset:1024
	s_waitcnt vmcnt(5) lgkmcnt(0)
	v_mfma_f32_16x16x32_bf16 v[66:69], v[74:77], v[66:69], v[70:73]
	s_nop 2
	ds_read_b128 v[70:73], v191 offset:1088
	s_waitcnt vmcnt(4) lgkmcnt(0)
	v_mfma_f32_16x16x32_bf16 v[62:65], v[70:73], v[62:65], v[66:69]
	s_nop 2
	ds_read_b128 v[66:69], v191 offset:1152
	s_waitcnt vmcnt(3) lgkmcnt(0)
	v_mfma_f32_16x16x32_bf16 v[58:61], v[66:69], v[58:61], v[62:65]
	s_nop 2
	ds_read_b128 v[62:65], v191 offset:1216
	s_waitcnt vmcnt(2) lgkmcnt(0)
	v_mfma_f32_16x16x32_bf16 v[54:57], v[62:65], v[54:57], v[58:61]
	s_nop 2
	ds_read_b128 v[58:61], v191 offset:1280
	s_waitcnt vmcnt(1) lgkmcnt(0)
	v_mfma_f32_16x16x32_bf16 v[50:53], v[58:61], v[50:53], v[54:57]
	s_nop 2
	ds_read_b128 v[54:57], v191 offset:1344
	s_waitcnt vmcnt(0) lgkmcnt(0)
	v_mfma_f32_16x16x32_bf16 v[46:49], v[54:57], v[46:49], v[50:53]
	s_nop 7
	ds_write_b128 v0, v[46:49]
	s_waitcnt lgkmcnt(0)
	s_waitcnt lgkmcnt(0)
	s_barrier
	s_cbranch_vccnz .LBB11_2870
	v_readlane_b32 s0, v245, 40
	s_nop 1
	v_add_u32_e32 v0, s0, v158
	ds_read_b128 v[50:53], v0 offset:2048
	s_lshl_b32 s0, s9, 17
	s_waitcnt lgkmcnt(0)
	v_pk_add_f32 v[52:53], v[48:49], v[52:53]
	v_pk_add_f32 v[50:51], v[46:47], v[50:51]
	ds_read_b128 v[46:49], v0 offset:4096
	s_waitcnt lgkmcnt(0)
	v_pk_add_f32 v[52:53], v[52:53], v[48:49]
	v_pk_add_f32 v[50:51], v[50:51], v[46:47]
	ds_read_b128 v[46:49], v0 offset:6144
	v_subrev_u32_e32 v0, s0, v173
	s_waitcnt lgkmcnt(0)
	v_pk_add_f32 v[46:47], v[50:51], v[46:47]
	v_add_u32_e32 v50, s40, v159
	v_pk_add_f32 v[48:49], v[52:53], v[48:49]
	v_ashrrev_i32_e32 v51, 31, v50
	v_lshlrev_b64 v[52:53], 1, v[0:1]
	v_lshl_add_u64 v[54:55], s[66:67], 0, v[52:53]
	v_lshlrev_b64 v[50:51], 1, v[50:51]
	v_lshl_add_u64 v[54:55], v[54:55], 0, v[50:51]
	v_lshl_add_u64 v[52:53], s[64:65], 0, v[52:53]
	v_lshl_add_u64 v[50:51], v[52:53], 0, v[50:51]
	global_load_dwordx2 v[52:53], v[54:55], off
	global_load_dwordx2 v[56:57], v[50:51], off
	s_waitcnt vmcnt(1)
	v_lshlrev_b32_e32 v58, 16, v52
	v_and_b32_e32 v59, 0xffff0000, v52
	s_waitcnt vmcnt(0)
	v_lshlrev_b32_e32 v60, 16, v56
	v_and_b32_e32 v61, 0xffff0000, v56
	v_lshlrev_b32_e32 v52, 16, v53
	v_and_b32_e32 v53, 0xffff0000, v53
	v_lshlrev_b32_e32 v56, 16, v57
	v_and_b32_e32 v57, 0xffff0000, v57
	v_pk_add_f32 v[58:59], v[58:59], v[60:61]
	v_pk_add_f32 v[52:53], v[52:53], v[56:57]
	v_pk_fma_f32 v[46:47], v[46:47], 0.5, v[58:59] op_sel_hi:[1,0,1]
	v_pk_fma_f32 v[48:49], v[48:49], 0.5, v[52:53] op_sel_hi:[1,0,1]
	v_cvt_pk_bf16_f32 v52, v46, v47
	s_nop 0
	v_cvt_pk_bf16_f32 v53, v48, v49
	v_lshlrev_b32_e32 v56, 16, v52
	v_and_b32_e32 v57, 0xffff0000, v52
	v_lshlrev_b32_e32 v58, 16, v53
	v_and_b32_e32 v59, 0xffff0000, v53
	v_sub_f32_e32 v0, v48, v58
	v_sub_f32_e32 v48, v49, v59
	v_sub_f32_e32 v46, v46, v56
	v_sub_f32_e32 v47, v47, v57
	v_cvt_pk_bf16_f32 v46, v46, v47
	v_cvt_pk_bf16_f32 v47, v0, v48
	global_store_dwordx2 v[54:55], v[52:53], off sc1
	global_store_dwordx2 v[50:51], v[46:47], off sc1
	v_lshlrev_b32_e32 v48, 16, v46
	v_and_b32_e32 v49, 0xffff0000, v46
	v_lshlrev_b32_e32 v60, 16, v47
	v_and_b32_e32 v61, 0xffff0000, v47
	v_pk_add_f32 v[58:59], v[58:59], v[60:61]
	v_pk_add_f32 v[48:49], v[56:57], v[48:49]
	v_mul_f32_e32 v46, v59, v59
	v_mul_f32_e32 v0, v49, v49
	v_fmac_f32_e32 v0, v48, v48
	v_fmac_f32_e32 v46, v58, v58
	v_add_f32_e32 v0, v0, v46
	ds_bpermute_b32 v46, v204, v0
	s_waitcnt lgkmcnt(0)
	v_add_f32_e32 v46, v0, v46
	ds_bpermute_b32 v47, v205, v46
	s_and_saveexec_b64 s[38:39], s[10:11]
	s_cbranch_execz .LBB11_2869
	s_lshl_b32 s0, s9, 7
	v_subrev_u32_e32 v0, s0, v172
	v_lshl_add_u64 v[48:49], v[0:1], 2, s[36:37]
	s_waitcnt lgkmcnt(0)
	v_add_f32_e32 v0, v46, v47
	global_atomic_add_f32 v[48:49], v0, off
	s_branch .LBB11_2869
